# GEMM phases: the 16 fragment reads of each unit's first load segment are issued at the top of the unit loop, overlapping the unit scheduler's scalar code (plus hoisted B-fragment base register)
# speedup vs baseline: 1.0071x; 1.0024x over previous
.LBB0_292:
	v_add_u32_e32 v145, 0x10000, v168
	ds_read_b128 v[80:83], v145
	ds_read_b128 v[116:119], v145 offset:1024
	ds_read_b128 v[136:139], v145 offset:2048
	ds_read_b128 v[140:143], v145 offset:3072
	ds_read_b128 v[158:161], v145 offset:16384
	ds_read_b128 v[162:165], v145 offset:17408
	ds_read_b128 v[170:173], v145 offset:18432
	ds_read_b128 v[174:177], v145 offset:19456
	ds_read_b128 v[178:181], v169
	ds_read_b128 v[182:185], v169 offset:1024
	ds_read_b128 v[186:189], v169 offset:2048
	ds_read_b128 v[190:193], v169 offset:3072
	ds_read_b128 v[194:197], v169 offset:4096
	ds_read_b128 v[198:201], v169 offset:5120
	ds_read_b128 v[202:205], v169 offset:6144
	ds_read_b128 v[206:209], v169 offset:7168
	s_add_i32 s54, s21, 1
	s_mul_i32 s4, s54, s41
	s_mul_hi_u32 s5, s54, s0
	s_add_i32 s5, s5, s4
	s_mul_i32 s4, s54, s0
	s_add_u32 s72, s4, s1
	s_addc_u32 s73, s5, s53
	v_cmp_gt_i64_e32 vcc, s[72:73], v[228:229]
	v_cmp_lt_i64_e64 s[4:5], s[72:73], v[220:221]
	s_cbranch_vccnz .LBB0_294
	s_ashr_i32 s20, s72, 31
	s_lshr_b32 s20, s20, 29
	s_add_i32 s20, s72, s20
	s_ashr_i32 s22, s20, 3
	s_and_b32 s20, s20, -8
	s_sub_i32 s20, s72, s20
	s_cmp_lt_i32 s20, 0
	s_movk_i32 s23, 0x111
	s_cselect_b32 s23, s23, 0x110
	s_mul_i32 s20, s20, s23
	s_add_i32 s20, s20, s22
	s_ashr_i32 s22, s20, 31
	s_lshr_b32 s22, s22, 26
	s_add_i32 s22, s20, s22
	s_ashr_i32 s23, s22, 6
	s_lshl_b32 s23, s23, 2
	s_sub_i32 s55, 0x88, s23
	s_min_i32 s55, s55, 4
	s_abs_i32 s56, s55
	v_cvt_f32_u32_e32 v0, s56
	s_sub_i32 s60, 0, s56
	s_andn2_b32 s22, s22, 63
	s_sub_i32 s22, s20, s22
	v_rcp_iflag_f32_e32 v0, v0
	s_abs_i32 s20, s22
	s_xor_b32 s57, s22, s55
	s_ashr_i32 s57, s57, 31
	v_mul_f32_e32 v0, 0x4f7ffffe, v0
	v_cvt_u32_f32_e32 v0, v0
	s_nop 0
	v_readfirstlane_b32 s61, v0
	s_mul_i32 s60, s60, s61
	s_mul_hi_u32 s60, s61, s60
	s_add_i32 s61, s61, s60
	s_mul_hi_u32 s60, s20, s61
	s_mul_i32 s61, s60, s56
	s_sub_i32 s20, s20, s61
	s_add_i32 s67, s60, 1
	s_sub_i32 s61, s20, s56
	s_cmp_ge_u32 s20, s56
	s_cselect_b32 s60, s67, s60
	s_cselect_b32 s20, s61, s20
	s_add_i32 s61, s60, 1
	s_cmp_ge_u32 s20, s56
	s_cselect_b32 s20, s61, s60
	s_xor_b32 s20, s20, s57
	s_sub_i32 s20, s20, s57
	s_mul_i32 s55, s20, s55
	s_sub_i32 s22, s22, s55
	s_add_i32 s22, s23, s22

.LBB0_296:
	s_ashr_i32 s23, s22, 31
	s_lshl_b64 s[56:57], s[22:23], 21
	s_add_u32 s72, s2, s56
	s_addc_u32 s73, s3, s57
	s_and_b64 s[56:57], s[4:5], exec
	s_cselect_b32 s23, s73, s81
	s_cselect_b32 s56, s72, s80
	s_ashr_i32 s21, s20, 31
	s_lshl_b64 s[60:61], s[20:21], 20
	s_add_u32 s74, s14, s60
	s_addc_u32 s75, s15, s61
	s_and_b64 s[60:61], s[4:5], exec
	s_cselect_b32 s21, s75, s83
	s_cselect_b32 s57, s74, s82
	s_add_u32 s80, s80, 0x100080
	s_addc_u32 s81, s81, 0
	s_add_u32 s60, s82, 0x100
	s_addc_u32 s61, s83, 0
	s_mov_b32 s68, -2
	s_add_u32 s67, s80, 0xfff00080
	s_addc_u32 s69, s81, -1
	s_add_i32 s70, 0, 0x10000
	s_cmp_eq_u32 s68, 28
	s_cselect_b32 s85, s23, s69
	s_cselect_b32 s84, s56, s67
	s_cselect_b32 s83, s21, s61
	s_cselect_b32 s82, s57, s60
	s_add_i32 s67, 0, 0x14000
	s_add_i32 m0, s26, 0xc000
	global_load_lds_dwordx4 v154, s[80:81]
	s_add_i32 m0, s26, 0xe000
	s_nop 0
	global_load_lds_dwordx4 v156, s[80:81]
	s_waitcnt vmcnt(8)
	s_waitcnt lgkmcnt(0)
	s_barrier
	s_waitcnt lgkmcnt(0)
	v_mfma_f32_16x16x32_bf16 v[132:135], v[80:83], v[178:181], 0
	v_mfma_f32_16x16x32_bf16 v[132:135], v[116:119], v[182:185], v[132:135]
	v_mfma_f32_16x16x32_bf16 v[124:127], v[158:161], v[178:181], 0
	v_mfma_f32_16x16x32_bf16 v[124:127], v[162:165], v[182:185], v[124:127]
	v_mfma_f32_16x16x32_bf16 v[128:131], v[136:139], v[178:181], 0
	v_mfma_f32_16x16x32_bf16 v[128:131], v[140:143], v[182:185], v[128:131]
	v_mfma_f32_16x16x32_bf16 v[120:123], v[170:173], v[178:181], 0
	v_mfma_f32_16x16x32_bf16 v[120:123], v[174:177], v[182:185], v[120:123]
	v_mfma_f32_16x16x32_bf16 v[112:115], v[80:83], v[186:189], 0
	v_mfma_f32_16x16x32_bf16 v[112:115], v[116:119], v[190:193], v[112:115]
	v_mfma_f32_16x16x32_bf16 v[104:107], v[158:161], v[186:189], 0
	v_mfma_f32_16x16x32_bf16 v[104:107], v[162:165], v[190:193], v[104:107]
	v_mfma_f32_16x16x32_bf16 v[108:111], v[136:139], v[186:189], 0
	v_mfma_f32_16x16x32_bf16 v[108:111], v[140:143], v[190:193], v[108:111]
	v_mfma_f32_16x16x32_bf16 v[100:103], v[170:173], v[186:189], 0
	v_mfma_f32_16x16x32_bf16 v[100:103], v[174:177], v[190:193], v[100:103]
	v_mfma_f32_16x16x32_bf16 v[96:99], v[80:83], v[194:197], 0
	v_mfma_f32_16x16x32_bf16 v[96:99], v[116:119], v[198:201], v[96:99]
	v_mfma_f32_16x16x32_bf16 v[88:91], v[158:161], v[194:197], 0
	v_mfma_f32_16x16x32_bf16 v[88:91], v[162:165], v[198:201], v[88:91]
	v_mfma_f32_16x16x32_bf16 v[92:95], v[136:139], v[194:197], 0
	v_mfma_f32_16x16x32_bf16 v[92:95], v[140:143], v[198:201], v[92:95]
	v_mfma_f32_16x16x32_bf16 v[84:87], v[170:173], v[194:197], 0
	v_mfma_f32_16x16x32_bf16 v[84:87], v[174:177], v[198:201], v[84:87]
	v_mfma_f32_16x16x32_bf16 v[76:79], v[80:83], v[202:205], 0
	v_mfma_f32_16x16x32_bf16 v[76:79], v[116:119], v[206:209], v[76:79]
	v_mfma_f32_16x16x32_bf16 v[68:71], v[158:161], v[202:205], 0
	v_mfma_f32_16x16x32_bf16 v[68:71], v[162:165], v[206:209], v[68:71]
	v_mfma_f32_16x16x32_bf16 v[72:75], v[136:139], v[202:205], 0
	v_mfma_f32_16x16x32_bf16 v[72:75], v[140:143], v[206:209], v[72:75]
	v_mfma_f32_16x16x32_bf16 v[64:67], v[170:173], v[202:205], 0
	v_mfma_f32_16x16x32_bf16 v[64:67], v[174:177], v[206:209], v[64:67]
	s_barrier
	s_add_i32 s69, s70, s24
	s_mov_b32 m0, s69
	ds_read_b128 v[178:181], v169 offset:16384
	ds_read_b128 v[182:185], v169 offset:17408
	ds_read_b128 v[186:189], v169 offset:18432
	ds_read_b128 v[190:193], v169 offset:19456
	ds_read_b128 v[194:197], v169 offset:20480
	ds_read_b128 v[198:201], v169 offset:21504
	ds_read_b128 v[202:205], v169 offset:22528
	ds_read_b128 v[206:209], v169 offset:23552
	global_load_lds_dwordx4 v146, s[82:83]
	s_add_i32 m0, s69, 0x2000
	s_add_u32 s70, s82, 0x80000
	s_addc_u32 s71, s83, 0
	s_add_i32 s67, s67, s24
	global_load_lds_dwordx4 v150, s[82:83]
	s_mov_b32 m0, s67
	s_nop 0
	global_load_lds_dwordx4 v146, s[70:71]
	s_add_i32 m0, s67, 0x2000
	s_nop 0
	global_load_lds_dwordx4 v150, s[70:71]
	s_mov_b32 m0, s26
	s_nop 0
	global_load_lds_dwordx4 v144, s[84:85]
	s_mov_b32 m0, s28
	s_nop 0
	global_load_lds_dwordx4 v148, s[84:85]
	s_waitcnt vmcnt(8)
	s_waitcnt lgkmcnt(0)
	s_barrier
	s_waitcnt lgkmcnt(0)
	v_mfma_f32_16x16x32_bf16 v[60:63], v[80:83], v[178:181], 0
	v_mfma_f32_16x16x32_bf16 v[60:63], v[116:119], v[182:185], v[60:63]
	v_mfma_f32_16x16x32_bf16 v[52:55], v[158:161], v[178:181], 0
	v_mfma_f32_16x16x32_bf16 v[52:55], v[162:165], v[182:185], v[52:55]
	v_mfma_f32_16x16x32_bf16 v[56:59], v[136:139], v[178:181], 0
	v_mfma_f32_16x16x32_bf16 v[56:59], v[140:143], v[182:185], v[56:59]
	v_mfma_f32_16x16x32_bf16 v[48:51], v[170:173], v[178:181], 0
	v_mfma_f32_16x16x32_bf16 v[48:51], v[174:177], v[182:185], v[48:51]
	v_mfma_f32_16x16x32_bf16 v[44:47], v[80:83], v[186:189], 0
	v_mfma_f32_16x16x32_bf16 v[44:47], v[116:119], v[190:193], v[44:47]
	v_mfma_f32_16x16x32_bf16 v[36:39], v[158:161], v[186:189], 0
	v_mfma_f32_16x16x32_bf16 v[36:39], v[162:165], v[190:193], v[36:39]
	v_mfma_f32_16x16x32_bf16 v[40:43], v[136:139], v[186:189], 0
	v_mfma_f32_16x16x32_bf16 v[40:43], v[140:143], v[190:193], v[40:43]
	v_mfma_f32_16x16x32_bf16 v[32:35], v[170:173], v[186:189], 0
	v_mfma_f32_16x16x32_bf16 v[32:35], v[174:177], v[190:193], v[32:35]
	v_mfma_f32_16x16x32_bf16 v[28:31], v[80:83], v[194:197], 0
	v_mfma_f32_16x16x32_bf16 v[28:31], v[116:119], v[198:201], v[28:31]
	v_mfma_f32_16x16x32_bf16 v[20:23], v[158:161], v[194:197], 0
	v_mfma_f32_16x16x32_bf16 v[20:23], v[162:165], v[198:201], v[20:23]
	v_mfma_f32_16x16x32_bf16 v[24:27], v[136:139], v[194:197], 0
	v_mfma_f32_16x16x32_bf16 v[24:27], v[140:143], v[198:201], v[24:27]
	v_mfma_f32_16x16x32_bf16 v[16:19], v[170:173], v[194:197], 0
	v_mfma_f32_16x16x32_bf16 v[16:19], v[174:177], v[198:201], v[16:19]
	v_mfma_f32_16x16x32_bf16 v[12:15], v[80:83], v[202:205], 0
	v_mfma_f32_16x16x32_bf16 v[12:15], v[116:119], v[206:209], v[12:15]
	v_mfma_f32_16x16x32_bf16 v[4:7], v[158:161], v[202:205], 0
	v_mfma_f32_16x16x32_bf16 v[4:7], v[162:165], v[206:209], v[4:7]
	v_mfma_f32_16x16x32_bf16 v[8:11], v[136:139], v[202:205], 0
	v_mfma_f32_16x16x32_bf16 v[8:11], v[140:143], v[206:209], v[8:11]
	v_mfma_f32_16x16x32_bf16 v[0:3], v[170:173], v[202:205], 0
	v_mfma_f32_16x16x32_bf16 v[0:3], v[174:177], v[206:209], v[0:3]
	s_barrier
	s_add_i32 s67, 0, 0x18000
	s_add_i32 s69, 0, 0x1c000
	ds_read_b128 v[80:83], v145 offset:32768
	ds_read_b128 v[116:119], v145 offset:33792
	ds_read_b128 v[136:139], v145 offset:34816
	ds_read_b128 v[140:143], v145 offset:35840
	ds_read_b128 v[158:161], v145 offset:49152
	ds_read_b128 v[162:165], v145 offset:50176
	ds_read_b128 v[170:173], v145 offset:51200
	ds_read_b128 v[174:177], v145 offset:52224
	s_add_u32 s70, s84, 0x100000
	s_addc_u32 s71, s85, 0
	s_mov_b32 m0, s29
	ds_read_b128 v[178:181], v169 offset:32768
	ds_read_b128 v[182:185], v169 offset:33792
	ds_read_b128 v[186:189], v169 offset:34816
	ds_read_b128 v[190:193], v169 offset:35840
	ds_read_b128 v[194:197], v169 offset:36864
	ds_read_b128 v[198:201], v169 offset:37888
	ds_read_b128 v[202:205], v169 offset:38912
	ds_read_b128 v[206:209], v169 offset:39936
	global_load_lds_dwordx4 v144, s[70:71]
	s_mov_b32 m0, s34
	s_nop 0
	global_load_lds_dwordx4 v148, s[70:71]
	s_waitcnt vmcnt(8)
	s_waitcnt lgkmcnt(0)
	s_barrier
	s_waitcnt lgkmcnt(0)
	v_mfma_f32_16x16x32_bf16 v[132:135], v[80:83], v[178:181], v[132:135]
	v_mfma_f32_16x16x32_bf16 v[132:135], v[116:119], v[182:185], v[132:135]
	v_mfma_f32_16x16x32_bf16 v[124:127], v[158:161], v[178:181], v[124:127]
	v_mfma_f32_16x16x32_bf16 v[124:127], v[162:165], v[182:185], v[124:127]
	v_mfma_f32_16x16x32_bf16 v[128:131], v[136:139], v[178:181], v[128:131]
	v_mfma_f32_16x16x32_bf16 v[128:131], v[140:143], v[182:185], v[128:131]
	v_mfma_f32_16x16x32_bf16 v[120:123], v[170:173], v[178:181], v[120:123]
	v_mfma_f32_16x16x32_bf16 v[120:123], v[174:177], v[182:185], v[120:123]
	v_mfma_f32_16x16x32_bf16 v[112:115], v[80:83], v[186:189], v[112:115]
	v_mfma_f32_16x16x32_bf16 v[112:115], v[116:119], v[190:193], v[112:115]
	v_mfma_f32_16x16x32_bf16 v[104:107], v[158:161], v[186:189], v[104:107]
	v_mfma_f32_16x16x32_bf16 v[104:107], v[162:165], v[190:193], v[104:107]
	v_mfma_f32_16x16x32_bf16 v[108:111], v[136:139], v[186:189], v[108:111]
	v_mfma_f32_16x16x32_bf16 v[108:111], v[140:143], v[190:193], v[108:111]
	v_mfma_f32_16x16x32_bf16 v[100:103], v[170:173], v[186:189], v[100:103]
	v_mfma_f32_16x16x32_bf16 v[100:103], v[174:177], v[190:193], v[100:103]
	v_mfma_f32_16x16x32_bf16 v[96:99], v[80:83], v[194:197], v[96:99]
	v_mfma_f32_16x16x32_bf16 v[96:99], v[116:119], v[198:201], v[96:99]
	v_mfma_f32_16x16x32_bf16 v[88:91], v[158:161], v[194:197], v[88:91]
	v_mfma_f32_16x16x32_bf16 v[88:91], v[162:165], v[198:201], v[88:91]
	v_mfma_f32_16x16x32_bf16 v[92:95], v[136:139], v[194:197], v[92:95]
	v_mfma_f32_16x16x32_bf16 v[92:95], v[140:143], v[198:201], v[92:95]
	v_mfma_f32_16x16x32_bf16 v[84:87], v[170:173], v[194:197], v[84:87]
	v_mfma_f32_16x16x32_bf16 v[84:87], v[174:177], v[198:201], v[84:87]
	v_mfma_f32_16x16x32_bf16 v[76:79], v[80:83], v[202:205], v[76:79]
	v_mfma_f32_16x16x32_bf16 v[76:79], v[116:119], v[206:209], v[76:79]
	v_mfma_f32_16x16x32_bf16 v[68:71], v[158:161], v[202:205], v[68:71]
	v_mfma_f32_16x16x32_bf16 v[68:71], v[162:165], v[206:209], v[68:71]
	v_mfma_f32_16x16x32_bf16 v[72:75], v[136:139], v[202:205], v[72:75]
	v_mfma_f32_16x16x32_bf16 v[72:75], v[140:143], v[206:209], v[72:75]
	v_mfma_f32_16x16x32_bf16 v[64:67], v[170:173], v[202:205], v[64:67]
	v_mfma_f32_16x16x32_bf16 v[64:67], v[174:177], v[206:209], v[64:67]
	s_barrier
	s_add_i32 s67, s67, s24
	s_add_u32 s98, s82, 0x80
	s_addc_u32 s99, s83, 0
	s_mov_b32 m0, s67
	ds_read_b128 v[178:181], v169 offset:49152
	ds_read_b128 v[182:185], v169 offset:50176
	ds_read_b128 v[186:189], v169 offset:51200
	ds_read_b128 v[190:193], v169 offset:52224
	ds_read_b128 v[194:197], v169 offset:53248
	ds_read_b128 v[198:201], v169 offset:54272
	ds_read_b128 v[202:205], v169 offset:55296
	ds_read_b128 v[206:209], v169 offset:56320
	global_load_lds_dwordx4 v146, s[98:99]
	s_add_i32 m0, s67, 0x2000
	s_add_u32 s70, s82, 0x80080
	s_addc_u32 s71, s83, 0
	s_add_i32 s67, s69, s24
	global_load_lds_dwordx4 v150, s[98:99]
	s_mov_b32 m0, s67
	s_nop 0
	global_load_lds_dwordx4 v146, s[70:71]
	s_add_i32 m0, s67, 0x2000
	s_nop 0
	global_load_lds_dwordx4 v150, s[70:71]
	s_add_u32 s98, s84, 0x80
	s_addc_u32 s99, s85, 0
	s_mov_b32 m0, s39
	s_nop 0
	global_load_lds_dwordx4 v144, s[98:99]
	s_mov_b32 m0, s40
	s_nop 0
	global_load_lds_dwordx4 v148, s[98:99]
	s_waitcnt vmcnt(8)
	s_waitcnt lgkmcnt(0)
	s_barrier
	s_waitcnt lgkmcnt(0)
	v_mfma_f32_16x16x32_bf16 v[60:63], v[80:83], v[178:181], v[60:63]
	v_mfma_f32_16x16x32_bf16 v[60:63], v[116:119], v[182:185], v[60:63]
	v_mfma_f32_16x16x32_bf16 v[52:55], v[158:161], v[178:181], v[52:55]
	v_mfma_f32_16x16x32_bf16 v[52:55], v[162:165], v[182:185], v[52:55]
	v_mfma_f32_16x16x32_bf16 v[56:59], v[136:139], v[178:181], v[56:59]
	v_mfma_f32_16x16x32_bf16 v[56:59], v[140:143], v[182:185], v[56:59]
	v_mfma_f32_16x16x32_bf16 v[48:51], v[170:173], v[178:181], v[48:51]
	v_mfma_f32_16x16x32_bf16 v[48:51], v[174:177], v[182:185], v[48:51]
	v_mfma_f32_16x16x32_bf16 v[44:47], v[80:83], v[186:189], v[44:47]
	v_mfma_f32_16x16x32_bf16 v[44:47], v[116:119], v[190:193], v[44:47]
	v_mfma_f32_16x16x32_bf16 v[36:39], v[158:161], v[186:189], v[36:39]
	v_mfma_f32_16x16x32_bf16 v[36:39], v[162:165], v[190:193], v[36:39]
	v_mfma_f32_16x16x32_bf16 v[40:43], v[136:139], v[186:189], v[40:43]
	v_mfma_f32_16x16x32_bf16 v[40:43], v[140:143], v[190:193], v[40:43]
	v_mfma_f32_16x16x32_bf16 v[32:35], v[170:173], v[186:189], v[32:35]
	v_mfma_f32_16x16x32_bf16 v[32:35], v[174:177], v[190:193], v[32:35]
	v_mfma_f32_16x16x32_bf16 v[28:31], v[80:83], v[194:197], v[28:31]
	v_mfma_f32_16x16x32_bf16 v[28:31], v[116:119], v[198:201], v[28:31]
	v_mfma_f32_16x16x32_bf16 v[20:23], v[158:161], v[194:197], v[20:23]
	v_mfma_f32_16x16x32_bf16 v[20:23], v[162:165], v[198:201], v[20:23]
	v_mfma_f32_16x16x32_bf16 v[24:27], v[136:139], v[194:197], v[24:27]
	v_mfma_f32_16x16x32_bf16 v[24:27], v[140:143], v[198:201], v[24:27]
	v_mfma_f32_16x16x32_bf16 v[16:19], v[170:173], v[194:197], v[16:19]
	v_mfma_f32_16x16x32_bf16 v[16:19], v[174:177], v[198:201], v[16:19]
	v_mfma_f32_16x16x32_bf16 v[12:15], v[80:83], v[202:205], v[12:15]
	v_mfma_f32_16x16x32_bf16 v[12:15], v[116:119], v[206:209], v[12:15]
	v_mfma_f32_16x16x32_bf16 v[4:7], v[158:161], v[202:205], v[4:7]
	v_mfma_f32_16x16x32_bf16 v[4:7], v[162:165], v[206:209], v[4:7]
	v_mfma_f32_16x16x32_bf16 v[8:11], v[136:139], v[202:205], v[8:11]
	v_mfma_f32_16x16x32_bf16 v[8:11], v[140:143], v[206:209], v[8:11]
	v_mfma_f32_16x16x32_bf16 v[0:3], v[170:173], v[202:205], v[0:3]
	v_mfma_f32_16x16x32_bf16 v[0:3], v[174:177], v[206:209], v[0:3]
	s_barrier
	s_add_i32 s68, s68, 2
	s_add_u32 s80, s80, 0x100
	s_addc_u32 s81, s81, 0
	s_add_u32 s60, s60, 0x100
	s_addc_u32 s61, s61, 0

.LBB0_374:
	v_add_u32_e32 v169, 0x10000, v186
	ds_read_b128 v[128:131], v169
	ds_read_b128 v[132:135], v169 offset:1024
	ds_read_b128 v[136:139], v169 offset:2048
	ds_read_b128 v[140:143], v169 offset:3072
	ds_read_b128 v[144:147], v169 offset:16384
	ds_read_b128 v[148:151], v169 offset:17408
	ds_read_b128 v[152:155], v169 offset:18432
	ds_read_b128 v[156:159], v169 offset:19456
	ds_read_b128 v[160:163], v187
	ds_read_b128 v[164:167], v187 offset:1024
	ds_read_b128 v[182:185], v187 offset:2048
	ds_read_b128 v[188:191], v187 offset:3072
	ds_read_b128 v[192:195], v187 offset:4096
	ds_read_b128 v[196:199], v187 offset:5120
	ds_read_b128 v[200:203], v187 offset:6144
	ds_read_b128 v[204:207], v187 offset:7168
	s_add_i32 s69, s23, 1
	s_mul_i32 s4, s69, s68
	s_mul_hi_u32 s5, s69, s0
	s_add_i32 s5, s5, s4
	s_mul_i32 s4, s69, s0
	s_add_u32 s74, s4, s1
	s_addc_u32 s75, s5, s28
	v_mov_b64_e32 v[0:1], 0x43f
	v_cmp_gt_i64_e32 vcc, s[74:75], v[0:1]
	v_cmp_lt_i64_e64 s[4:5], s[74:75], v[222:223]
	s_cbranch_vccnz .LBB0_376
	s_ashr_i32 s22, s74, 31
	s_lshr_b32 s22, s22, 29
	s_add_i32 s22, s74, s22
	s_ashr_i32 s67, s22, 3
	s_and_b32 s22, s22, -8
	s_sub_i32 s22, s74, s22
	s_cmp_lt_i32 s22, 0
	s_movk_i32 s71, 0x89
	s_cselect_b32 s71, s71, 0x88
	s_mul_i32 s22, s22, s71
	s_add_i32 s22, s22, s67
	s_ashr_i32 s67, s22, 31
	s_lshr_b32 s67, s67, 27
	s_add_i32 s67, s22, s67
	s_ashr_i32 s71, s67, 5
	s_lshl_b32 s71, s71, 2
	s_sub_i32 s72, 0x88, s71
	s_min_i32 s72, s72, 4
	s_abs_i32 s73, s72
	v_cvt_f32_u32_e32 v0, s73
	s_sub_i32 s75, 0, s73
	s_andn2_b32 s67, s67, 31
	s_sub_i32 s67, s22, s67
	v_rcp_iflag_f32_e32 v0, v0
	s_abs_i32 s22, s67
	s_xor_b32 s74, s67, s72
	s_ashr_i32 s74, s74, 31
	v_mul_f32_e32 v0, 0x4f7ffffe, v0
	v_cvt_u32_f32_e32 v0, v0
	s_nop 0
	v_readfirstlane_b32 s76, v0
	s_mul_i32 s75, s75, s76
	s_mul_hi_u32 s75, s76, s75
	s_add_i32 s76, s76, s75
	s_mul_hi_u32 s75, s22, s76
	s_mul_i32 s76, s75, s73
	s_sub_i32 s22, s22, s76
	s_add_i32 s77, s75, 1
	s_sub_i32 s76, s22, s73
	s_cmp_ge_u32 s22, s73
	s_cselect_b32 s75, s77, s75
	s_cselect_b32 s22, s76, s22
	s_add_i32 s76, s75, 1
	s_cmp_ge_u32 s22, s73
	s_cselect_b32 s22, s76, s75
	s_xor_b32 s22, s22, s74
	s_sub_i32 s22, s22, s74
	s_mul_i32 s72, s22, s72
	s_sub_i32 s67, s67, s72
	s_add_i32 s72, s71, s67

.LBB0_384:
	s_ashr_i32 s73, s72, 31
	s_lshl_b64 s[74:75], s[72:73], 20
	s_add_u32 s74, s2, s74
	s_addc_u32 s75, s3, s75
	s_and_b64 s[76:77], s[4:5], exec
	s_cselect_b32 s73, s75, s81
	s_cselect_b32 s79, s74, s80
	s_ashr_i32 s23, s22, 31
	s_lshl_b64 s[76:77], s[22:23], 20
	s_add_u32 s76, s14, s76
	s_addc_u32 s77, s15, s77
	s_and_b64 s[84:85], s[4:5], exec
	s_cselect_b32 s23, s77, s83
	s_cselect_b32 s86, s76, s82
	s_add_u32 s80, s80, 0x80080
	s_addc_u32 s81, s81, 0
	s_add_u32 s87, s82, 0x100
	s_addc_u32 s88, s83, 0
	s_mov_b32 s89, -2
	s_add_u32 s67, s80, 0xfff80080
	s_addc_u32 s82, s81, -1
	s_add_i32 s90, 0, 0x10000
	s_cmp_eq_u32 s89, 28
	s_cselect_b32 s85, s73, s82
	s_cselect_b32 s84, s79, s67
	s_cselect_b32 s83, s23, s88
	s_cselect_b32 s82, s86, s87
	s_add_i32 s67, 0, 0x14000
	s_add_i32 m0, s29, 0xc000
	global_load_lds_dwordx4 v178, s[80:81]
	s_add_i32 m0, s29, 0xe000
	s_nop 0
	global_load_lds_dwordx4 v180, s[80:81]
	s_waitcnt vmcnt(8)
	s_waitcnt lgkmcnt(0)
	s_barrier
	s_waitcnt lgkmcnt(0)
	v_mfma_f32_16x16x32_bf16 v[124:127], v[128:131], v[160:163], 0
	v_mfma_f32_16x16x32_bf16 v[124:127], v[132:135], v[164:167], v[124:127]
	v_mfma_f32_16x16x32_bf16 v[116:119], v[144:147], v[160:163], 0
	v_mfma_f32_16x16x32_bf16 v[116:119], v[148:151], v[164:167], v[116:119]
	v_mfma_f32_16x16x32_bf16 v[120:123], v[136:139], v[160:163], 0
	v_mfma_f32_16x16x32_bf16 v[120:123], v[140:143], v[164:167], v[120:123]
	v_mfma_f32_16x16x32_bf16 v[112:115], v[152:155], v[160:163], 0
	v_mfma_f32_16x16x32_bf16 v[112:115], v[156:159], v[164:167], v[112:115]
	v_mfma_f32_16x16x32_bf16 v[108:111], v[128:131], v[182:185], 0
	v_mfma_f32_16x16x32_bf16 v[108:111], v[132:135], v[188:191], v[108:111]
	v_mfma_f32_16x16x32_bf16 v[100:103], v[144:147], v[182:185], 0
	v_mfma_f32_16x16x32_bf16 v[100:103], v[148:151], v[188:191], v[100:103]
	v_mfma_f32_16x16x32_bf16 v[104:107], v[136:139], v[182:185], 0
	v_mfma_f32_16x16x32_bf16 v[104:107], v[140:143], v[188:191], v[104:107]
	v_mfma_f32_16x16x32_bf16 v[96:99], v[152:155], v[182:185], 0
	v_mfma_f32_16x16x32_bf16 v[96:99], v[156:159], v[188:191], v[96:99]
	v_mfma_f32_16x16x32_bf16 v[92:95], v[128:131], v[192:195], 0
	v_mfma_f32_16x16x32_bf16 v[92:95], v[132:135], v[196:199], v[92:95]
	v_mfma_f32_16x16x32_bf16 v[84:87], v[144:147], v[192:195], 0
	v_mfma_f32_16x16x32_bf16 v[84:87], v[148:151], v[196:199], v[84:87]
	v_mfma_f32_16x16x32_bf16 v[88:91], v[136:139], v[192:195], 0
	v_mfma_f32_16x16x32_bf16 v[88:91], v[140:143], v[196:199], v[88:91]
	v_mfma_f32_16x16x32_bf16 v[80:83], v[152:155], v[192:195], 0
	v_mfma_f32_16x16x32_bf16 v[80:83], v[156:159], v[196:199], v[80:83]
	v_mfma_f32_16x16x32_bf16 v[76:79], v[128:131], v[200:203], 0
	v_mfma_f32_16x16x32_bf16 v[76:79], v[132:135], v[204:207], v[76:79]
	v_mfma_f32_16x16x32_bf16 v[68:71], v[144:147], v[200:203], 0
	v_mfma_f32_16x16x32_bf16 v[68:71], v[148:151], v[204:207], v[68:71]
	v_mfma_f32_16x16x32_bf16 v[72:75], v[136:139], v[200:203], 0
	v_mfma_f32_16x16x32_bf16 v[72:75], v[140:143], v[204:207], v[72:75]
	v_mfma_f32_16x16x32_bf16 v[64:67], v[152:155], v[200:203], 0
	v_mfma_f32_16x16x32_bf16 v[64:67], v[156:159], v[204:207], v[64:67]
	s_barrier
	s_add_i32 s90, s90, s24
	s_mov_b32 m0, s90
	ds_read_b128 v[160:163], v187 offset:16384
	ds_read_b128 v[164:167], v187 offset:17408
	ds_read_b128 v[182:185], v187 offset:18432
	ds_read_b128 v[188:191], v187 offset:19456
	ds_read_b128 v[192:195], v187 offset:20480
	ds_read_b128 v[196:199], v187 offset:21504
	ds_read_b128 v[200:203], v187 offset:22528
	ds_read_b128 v[204:207], v187 offset:23552
	global_load_lds_dwordx4 v172, s[82:83]
	s_add_i32 m0, s90, 0x2000
	s_add_u32 s90, s82, 0x80000
	s_addc_u32 s91, s83, 0
	s_add_i32 s67, s67, s24
	global_load_lds_dwordx4 v168, s[82:83]
	s_mov_b32 m0, s67
	s_nop 0
	global_load_lds_dwordx4 v172, s[90:91]
	s_add_i32 m0, s67, 0x2000
	s_nop 0
	global_load_lds_dwordx4 v168, s[90:91]
	s_mov_b32 m0, s29
	s_nop 0
	global_load_lds_dwordx4 v174, s[84:85]
	s_mov_b32 m0, s34
	s_nop 0
	global_load_lds_dwordx4 v170, s[84:85]
	s_waitcnt vmcnt(8)
	s_waitcnt lgkmcnt(0)
	s_barrier
	s_waitcnt lgkmcnt(0)
	v_mfma_f32_16x16x32_bf16 v[60:63], v[128:131], v[160:163], 0
	v_mfma_f32_16x16x32_bf16 v[60:63], v[132:135], v[164:167], v[60:63]
	v_mfma_f32_16x16x32_bf16 v[52:55], v[144:147], v[160:163], 0
	v_mfma_f32_16x16x32_bf16 v[52:55], v[148:151], v[164:167], v[52:55]
	v_mfma_f32_16x16x32_bf16 v[56:59], v[136:139], v[160:163], 0
	v_mfma_f32_16x16x32_bf16 v[56:59], v[140:143], v[164:167], v[56:59]
	v_mfma_f32_16x16x32_bf16 v[48:51], v[152:155], v[160:163], 0
	v_mfma_f32_16x16x32_bf16 v[48:51], v[156:159], v[164:167], v[48:51]
	v_mfma_f32_16x16x32_bf16 v[44:47], v[128:131], v[182:185], 0
	v_mfma_f32_16x16x32_bf16 v[44:47], v[132:135], v[188:191], v[44:47]
	v_mfma_f32_16x16x32_bf16 v[36:39], v[144:147], v[182:185], 0
	v_mfma_f32_16x16x32_bf16 v[36:39], v[148:151], v[188:191], v[36:39]
	v_mfma_f32_16x16x32_bf16 v[40:43], v[136:139], v[182:185], 0
	v_mfma_f32_16x16x32_bf16 v[40:43], v[140:143], v[188:191], v[40:43]
	v_mfma_f32_16x16x32_bf16 v[32:35], v[152:155], v[182:185], 0
	v_mfma_f32_16x16x32_bf16 v[32:35], v[156:159], v[188:191], v[32:35]
	v_mfma_f32_16x16x32_bf16 v[28:31], v[128:131], v[192:195], 0
	v_mfma_f32_16x16x32_bf16 v[28:31], v[132:135], v[196:199], v[28:31]
	v_mfma_f32_16x16x32_bf16 v[20:23], v[144:147], v[192:195], 0
	v_mfma_f32_16x16x32_bf16 v[20:23], v[148:151], v[196:199], v[20:23]
	v_mfma_f32_16x16x32_bf16 v[24:27], v[136:139], v[192:195], 0
	v_mfma_f32_16x16x32_bf16 v[24:27], v[140:143], v[196:199], v[24:27]
	v_mfma_f32_16x16x32_bf16 v[16:19], v[152:155], v[192:195], 0
	v_mfma_f32_16x16x32_bf16 v[16:19], v[156:159], v[196:199], v[16:19]
	v_mfma_f32_16x16x32_bf16 v[12:15], v[128:131], v[200:203], 0
	v_mfma_f32_16x16x32_bf16 v[12:15], v[132:135], v[204:207], v[12:15]
	v_mfma_f32_16x16x32_bf16 v[4:7], v[144:147], v[200:203], 0
	v_mfma_f32_16x16x32_bf16 v[4:7], v[148:151], v[204:207], v[4:7]
	v_mfma_f32_16x16x32_bf16 v[8:11], v[136:139], v[200:203], 0
	v_mfma_f32_16x16x32_bf16 v[8:11], v[140:143], v[204:207], v[8:11]
	v_mfma_f32_16x16x32_bf16 v[0:3], v[152:155], v[200:203], 0
	v_mfma_f32_16x16x32_bf16 v[0:3], v[156:159], v[204:207], v[0:3]
	s_barrier
	s_add_i32 s67, 0, 0x18000
	s_add_i32 s90, 0, 0x1c000
	ds_read_b128 v[128:131], v169 offset:32768
	ds_read_b128 v[132:135], v169 offset:33792
	ds_read_b128 v[136:139], v169 offset:34816
	ds_read_b128 v[140:143], v169 offset:35840
	ds_read_b128 v[144:147], v169 offset:49152
	ds_read_b128 v[148:151], v169 offset:50176
	ds_read_b128 v[152:155], v169 offset:51200
	ds_read_b128 v[156:159], v169 offset:52224
	s_add_u32 s84, s84, 0x80000
	s_addc_u32 s85, s85, 0
	s_mov_b32 m0, s35
	ds_read_b128 v[160:163], v187 offset:32768
	ds_read_b128 v[164:167], v187 offset:33792
	ds_read_b128 v[182:185], v187 offset:34816
	ds_read_b128 v[188:191], v187 offset:35840
	ds_read_b128 v[192:195], v187 offset:36864
	ds_read_b128 v[196:199], v187 offset:37888
	ds_read_b128 v[200:203], v187 offset:38912
	ds_read_b128 v[204:207], v187 offset:39936
	global_load_lds_dwordx4 v174, s[84:85]
	s_mov_b32 m0, s38
	s_nop 0
	global_load_lds_dwordx4 v170, s[84:85]
	s_waitcnt vmcnt(8)
	s_waitcnt lgkmcnt(0)
	s_barrier
	s_waitcnt lgkmcnt(0)
	v_mfma_f32_16x16x32_bf16 v[124:127], v[128:131], v[160:163], v[124:127]
	v_mfma_f32_16x16x32_bf16 v[124:127], v[132:135], v[164:167], v[124:127]
	v_mfma_f32_16x16x32_bf16 v[116:119], v[144:147], v[160:163], v[116:119]
	v_mfma_f32_16x16x32_bf16 v[116:119], v[148:151], v[164:167], v[116:119]
	v_mfma_f32_16x16x32_bf16 v[120:123], v[136:139], v[160:163], v[120:123]
	v_mfma_f32_16x16x32_bf16 v[120:123], v[140:143], v[164:167], v[120:123]
	v_mfma_f32_16x16x32_bf16 v[112:115], v[152:155], v[160:163], v[112:115]
	v_mfma_f32_16x16x32_bf16 v[112:115], v[156:159], v[164:167], v[112:115]
	v_mfma_f32_16x16x32_bf16 v[108:111], v[128:131], v[182:185], v[108:111]
	v_mfma_f32_16x16x32_bf16 v[108:111], v[132:135], v[188:191], v[108:111]
	v_mfma_f32_16x16x32_bf16 v[100:103], v[144:147], v[182:185], v[100:103]
	v_mfma_f32_16x16x32_bf16 v[100:103], v[148:151], v[188:191], v[100:103]
	v_mfma_f32_16x16x32_bf16 v[104:107], v[136:139], v[182:185], v[104:107]
	v_mfma_f32_16x16x32_bf16 v[104:107], v[140:143], v[188:191], v[104:107]
	v_mfma_f32_16x16x32_bf16 v[96:99], v[152:155], v[182:185], v[96:99]
	v_mfma_f32_16x16x32_bf16 v[96:99], v[156:159], v[188:191], v[96:99]
	v_mfma_f32_16x16x32_bf16 v[92:95], v[128:131], v[192:195], v[92:95]
	v_mfma_f32_16x16x32_bf16 v[92:95], v[132:135], v[196:199], v[92:95]
	v_mfma_f32_16x16x32_bf16 v[84:87], v[144:147], v[192:195], v[84:87]
	v_mfma_f32_16x16x32_bf16 v[84:87], v[148:151], v[196:199], v[84:87]
	v_mfma_f32_16x16x32_bf16 v[88:91], v[136:139], v[192:195], v[88:91]
	v_mfma_f32_16x16x32_bf16 v[88:91], v[140:143], v[196:199], v[88:91]
	v_mfma_f32_16x16x32_bf16 v[80:83], v[152:155], v[192:195], v[80:83]
	v_mfma_f32_16x16x32_bf16 v[80:83], v[156:159], v[196:199], v[80:83]
	v_mfma_f32_16x16x32_bf16 v[76:79], v[128:131], v[200:203], v[76:79]
	v_mfma_f32_16x16x32_bf16 v[76:79], v[132:135], v[204:207], v[76:79]
	v_mfma_f32_16x16x32_bf16 v[68:71], v[144:147], v[200:203], v[68:71]
	v_mfma_f32_16x16x32_bf16 v[68:71], v[148:151], v[204:207], v[68:71]
	v_mfma_f32_16x16x32_bf16 v[72:75], v[136:139], v[200:203], v[72:75]
	v_mfma_f32_16x16x32_bf16 v[72:75], v[140:143], v[204:207], v[72:75]
	v_mfma_f32_16x16x32_bf16 v[64:67], v[152:155], v[200:203], v[64:67]
	v_mfma_f32_16x16x32_bf16 v[64:67], v[156:159], v[204:207], v[64:67]
	s_barrier
	s_add_i32 s67, s67, s24
	s_add_u32 s98, s82, 0x80
	s_addc_u32 s99, s83, 0
	s_mov_b32 m0, s67
	ds_read_b128 v[160:163], v187 offset:49152
	ds_read_b128 v[164:167], v187 offset:50176
	ds_read_b128 v[182:185], v187 offset:51200
	ds_read_b128 v[188:191], v187 offset:52224
	ds_read_b128 v[192:195], v187 offset:53248
	ds_read_b128 v[196:199], v187 offset:54272
	ds_read_b128 v[200:203], v187 offset:55296
	ds_read_b128 v[204:207], v187 offset:56320
	global_load_lds_dwordx4 v172, s[98:99]
	s_add_i32 m0, s67, 0x2000
	s_add_u32 s82, s82, 0x80080
	s_addc_u32 s83, s83, 0
	s_add_i32 s67, s90, s24
	global_load_lds_dwordx4 v168, s[98:99]
	s_mov_b32 m0, s67
	s_nop 0
	global_load_lds_dwordx4 v172, s[82:83]
	s_add_i32 m0, s67, 0x2000
	s_nop 0
	global_load_lds_dwordx4 v168, s[82:83]
	s_add_u32 s98, s84, 0xfff80080
	s_addc_u32 s99, s85, -1
	s_mov_b32 m0, s54
	s_nop 0
	global_load_lds_dwordx4 v174, s[98:99]
	s_mov_b32 m0, s55
	s_nop 0
	global_load_lds_dwordx4 v170, s[98:99]
	s_waitcnt vmcnt(8)
	s_waitcnt lgkmcnt(0)
	s_barrier
	s_waitcnt lgkmcnt(0)
	v_mfma_f32_16x16x32_bf16 v[60:63], v[128:131], v[160:163], v[60:63]
	v_mfma_f32_16x16x32_bf16 v[60:63], v[132:135], v[164:167], v[60:63]
	v_mfma_f32_16x16x32_bf16 v[52:55], v[144:147], v[160:163], v[52:55]
	v_mfma_f32_16x16x32_bf16 v[52:55], v[148:151], v[164:167], v[52:55]
	v_mfma_f32_16x16x32_bf16 v[56:59], v[136:139], v[160:163], v[56:59]
	v_mfma_f32_16x16x32_bf16 v[56:59], v[140:143], v[164:167], v[56:59]
	v_mfma_f32_16x16x32_bf16 v[48:51], v[152:155], v[160:163], v[48:51]
	v_mfma_f32_16x16x32_bf16 v[48:51], v[156:159], v[164:167], v[48:51]
	v_mfma_f32_16x16x32_bf16 v[44:47], v[128:131], v[182:185], v[44:47]
	v_mfma_f32_16x16x32_bf16 v[44:47], v[132:135], v[188:191], v[44:47]
	v_mfma_f32_16x16x32_bf16 v[36:39], v[144:147], v[182:185], v[36:39]
	v_mfma_f32_16x16x32_bf16 v[36:39], v[148:151], v[188:191], v[36:39]
	v_mfma_f32_16x16x32_bf16 v[40:43], v[136:139], v[182:185], v[40:43]
	v_mfma_f32_16x16x32_bf16 v[40:43], v[140:143], v[188:191], v[40:43]
	v_mfma_f32_16x16x32_bf16 v[32:35], v[152:155], v[182:185], v[32:35]
	v_mfma_f32_16x16x32_bf16 v[32:35], v[156:159], v[188:191], v[32:35]
	v_mfma_f32_16x16x32_bf16 v[28:31], v[128:131], v[192:195], v[28:31]
	v_mfma_f32_16x16x32_bf16 v[28:31], v[132:135], v[196:199], v[28:31]
	v_mfma_f32_16x16x32_bf16 v[20:23], v[144:147], v[192:195], v[20:23]
	v_mfma_f32_16x16x32_bf16 v[20:23], v[148:151], v[196:199], v[20:23]
	v_mfma_f32_16x16x32_bf16 v[24:27], v[136:139], v[192:195], v[24:27]
	v_mfma_f32_16x16x32_bf16 v[24:27], v[140:143], v[196:199], v[24:27]
	v_mfma_f32_16x16x32_bf16 v[16:19], v[152:155], v[192:195], v[16:19]
	v_mfma_f32_16x16x32_bf16 v[16:19], v[156:159], v[196:199], v[16:19]
	v_mfma_f32_16x16x32_bf16 v[12:15], v[128:131], v[200:203], v[12:15]
	v_mfma_f32_16x16x32_bf16 v[12:15], v[132:135], v[204:207], v[12:15]
	v_mfma_f32_16x16x32_bf16 v[4:7], v[144:147], v[200:203], v[4:7]
	v_mfma_f32_16x16x32_bf16 v[4:7], v[148:151], v[204:207], v[4:7]
	v_mfma_f32_16x16x32_bf16 v[8:11], v[136:139], v[200:203], v[8:11]
	v_mfma_f32_16x16x32_bf16 v[8:11], v[140:143], v[204:207], v[8:11]
	v_mfma_f32_16x16x32_bf16 v[0:3], v[152:155], v[200:203], v[0:3]
	v_mfma_f32_16x16x32_bf16 v[0:3], v[156:159], v[204:207], v[0:3]
	s_barrier
	s_add_i32 s89, s89, 2
	s_add_u32 s80, s80, 0x100
	s_addc_u32 s81, s81, 0
	s_add_u32 s87, s87, 0x100
	s_addc_u32 s88, s88, 0

.LBB0_580:
	v_add_u32_e32 v192, 0x10000, v238
	ds_read_b128 v[64:67], v192
	ds_read_b128 v[72:75], v192 offset:1024
	ds_read_b128 v[88:91], v192 offset:2048
	ds_read_b128 v[96:99], v192 offset:3072
	ds_read_b128 v[108:111], v192 offset:16384
	ds_read_b128 v[116:119], v192 offset:17408
	ds_read_b128 v[128:131], v192 offset:18432
	ds_read_b128 v[140:143], v192 offset:19456
	ds_read_b128 v[152:155], v240
	ds_read_b128 v[156:159], v240 offset:1024
	ds_read_b128 v[160:163], v240 offset:2048
	ds_read_b128 v[164:167], v240 offset:3072
	ds_read_b128 v[168:171], v240 offset:4096
	ds_read_b128 v[180:183], v240 offset:5120
	ds_read_b128 v[184:187], v240 offset:6144
	ds_read_b128 v[188:191], v240 offset:7168
	s_mov_b64 s[84:85], 0
	s_andn2_b64 vcc, exec, s[16:17]
	s_mov_b64 s[82:83], 0
	s_mov_b64 s[86:87], s[18:19]
	s_cbranch_vccz .LBB0_582
	s_andn2_b64 vcc, exec, s[86:87]
	s_add_i32 s54, s14, 1
	s_cbranch_vccz .LBB0_583
	s_branch .LBB0_585

.LBB0_594:
	s_ashr_i32 s81, s80, 31
	s_lshl_b64 s[84:85], s[80:81], 20
	s_add_u32 s84, s29, s84
	s_addc_u32 s85, s34, s85
	s_and_b64 s[86:87], s[82:83], exec
	s_cselect_b32 s81, s85, s95
	s_cselect_b32 vcc_lo, s84, s94
	s_ashr_i32 s79, s78, 31
	s_lshl_b64 s[86:87], s[78:79], 20
	s_add_u32 s86, s35, s86
	s_addc_u32 s87, s38, s87
	s_and_b64 s[2:3], s[82:83], exec
	s_cselect_b32 s79, s87, s93
	s_cselect_b32 vcc_hi, s86, s92
	s_lshl_b32 s88, s88, 8
	s_ashr_i32 s89, s88, 31
	s_lshl_b64 s[2:3], s[88:89], 2
	s_add_u32 s2, s90, s2
	s_addc_u32 s3, s91, s3
	s_add_i32 m0, s14, s41
	s_add_u32 s90, s94, 0x80080
	global_load_lds_dwordx4 v239, s[2:3]
	s_addc_u32 s91, s95, 0
	s_add_u32 s89, s92, 0x100
	s_addc_u32 s14, s93, 0
	s_mov_b32 s20, -2
	s_waitcnt vmcnt(0)
	s_add_u32 s2, s90, 0xfff80080
	s_addc_u32 s3, s91, -1
	s_add_i32 s67, 0, 0x10000
	s_cmp_eq_u32 s20, 28
	s_cselect_b32 s95, s81, s3
	s_cselect_b32 s94, vcc_lo, s2
	s_cselect_b32 s93, s79, s14
	s_cselect_b32 s92, vcc_hi, s89
	s_add_i32 s76, 0, 0x14000
	s_add_i32 m0, s39, 0xc000
	global_load_lds_dwordx4 v230, s[90:91]
	s_add_i32 m0, s39, 0xe000
	s_nop 0
	global_load_lds_dwordx4 v232, s[90:91]
	s_waitcnt vmcnt(8)
	s_waitcnt lgkmcnt(0)
	s_barrier
	s_waitcnt lgkmcnt(0)
	v_mfma_f32_16x16x32_bf16 v[176:179], v[64:67], v[152:155], 0
	v_mfma_f32_16x16x32_bf16 v[176:179], v[72:75], v[156:159], v[176:179]
	v_mfma_f32_16x16x32_bf16 v[148:151], v[108:111], v[152:155], 0
	v_mfma_f32_16x16x32_bf16 v[148:151], v[116:119], v[156:159], v[148:151]
	v_mfma_f32_16x16x32_bf16 v[172:175], v[88:91], v[152:155], 0
	v_mfma_f32_16x16x32_bf16 v[172:175], v[96:99], v[156:159], v[172:175]
	v_mfma_f32_16x16x32_bf16 v[144:147], v[128:131], v[152:155], 0
	v_mfma_f32_16x16x32_bf16 v[144:147], v[140:143], v[156:159], v[144:147]
	v_mfma_f32_16x16x32_bf16 v[136:139], v[64:67], v[160:163], 0
	v_mfma_f32_16x16x32_bf16 v[136:139], v[72:75], v[164:167], v[136:139]
	v_mfma_f32_16x16x32_bf16 v[124:127], v[108:111], v[160:163], 0
	v_mfma_f32_16x16x32_bf16 v[124:127], v[116:119], v[164:167], v[124:127]
	v_mfma_f32_16x16x32_bf16 v[132:135], v[88:91], v[160:163], 0
	v_mfma_f32_16x16x32_bf16 v[132:135], v[96:99], v[164:167], v[132:135]
	v_mfma_f32_16x16x32_bf16 v[120:123], v[128:131], v[160:163], 0
	v_mfma_f32_16x16x32_bf16 v[120:123], v[140:143], v[164:167], v[120:123]
	v_mfma_f32_16x16x32_bf16 v[112:115], v[64:67], v[168:171], 0
	v_mfma_f32_16x16x32_bf16 v[112:115], v[72:75], v[180:183], v[112:115]
	v_mfma_f32_16x16x32_bf16 v[100:103], v[108:111], v[168:171], 0
	v_mfma_f32_16x16x32_bf16 v[100:103], v[116:119], v[180:183], v[100:103]
	v_mfma_f32_16x16x32_bf16 v[104:107], v[88:91], v[168:171], 0
	v_mfma_f32_16x16x32_bf16 v[104:107], v[96:99], v[180:183], v[104:107]
	v_mfma_f32_16x16x32_bf16 v[92:95], v[128:131], v[168:171], 0
	v_mfma_f32_16x16x32_bf16 v[92:95], v[140:143], v[180:183], v[92:95]
	v_mfma_f32_16x16x32_bf16 v[84:87], v[64:67], v[184:187], 0
	v_mfma_f32_16x16x32_bf16 v[84:87], v[72:75], v[188:191], v[84:87]
	v_mfma_f32_16x16x32_bf16 v[76:79], v[108:111], v[184:187], 0
	v_mfma_f32_16x16x32_bf16 v[76:79], v[116:119], v[188:191], v[76:79]
	v_mfma_f32_16x16x32_bf16 v[80:83], v[88:91], v[184:187], 0
	v_mfma_f32_16x16x32_bf16 v[80:83], v[96:99], v[188:191], v[80:83]
	v_mfma_f32_16x16x32_bf16 v[68:71], v[128:131], v[184:187], 0
	v_mfma_f32_16x16x32_bf16 v[68:71], v[140:143], v[188:191], v[68:71]
	s_barrier
	s_add_i32 s2, s67, s28
	s_mov_b32 m0, s2
	ds_read_b128 v[152:155], v240 offset:16384
	ds_read_b128 v[156:159], v240 offset:17408
	ds_read_b128 v[160:163], v240 offset:18432
	ds_read_b128 v[164:167], v240 offset:19456
	ds_read_b128 v[168:171], v240 offset:20480
	ds_read_b128 v[180:183], v240 offset:21504
	ds_read_b128 v[184:187], v240 offset:22528
	ds_read_b128 v[188:191], v240 offset:23552
	global_load_lds_dwordx4 v216, s[92:93]
	s_add_i32 m0, s2, 0x2000
	s_add_u32 s2, s92, 0x80000
	s_addc_u32 s3, s93, 0
	s_add_i32 s67, s76, s28
	global_load_lds_dwordx4 v228, s[92:93]
	s_mov_b32 m0, s67
	s_nop 0
	global_load_lds_dwordx4 v216, s[2:3]
	s_add_i32 m0, s67, 0x2000
	s_nop 0
	global_load_lds_dwordx4 v228, s[2:3]
	s_mov_b32 m0, s39
	s_nop 0
	global_load_lds_dwordx4 v224, s[94:95]
	s_mov_b32 m0, s53
	s_nop 0
	global_load_lds_dwordx4 v226, s[94:95]
	s_waitcnt vmcnt(8)
	s_waitcnt lgkmcnt(0)
	s_barrier
	s_waitcnt lgkmcnt(0)
	v_mfma_f32_16x16x32_bf16 v[60:63], v[64:67], v[152:155], 0
	v_mfma_f32_16x16x32_bf16 v[60:63], v[72:75], v[156:159], v[60:63]
	v_mfma_f32_16x16x32_bf16 v[52:55], v[108:111], v[152:155], 0
	v_mfma_f32_16x16x32_bf16 v[52:55], v[116:119], v[156:159], v[52:55]
	v_mfma_f32_16x16x32_bf16 v[56:59], v[88:91], v[152:155], 0
	v_mfma_f32_16x16x32_bf16 v[56:59], v[96:99], v[156:159], v[56:59]
	v_mfma_f32_16x16x32_bf16 v[48:51], v[128:131], v[152:155], 0
	v_mfma_f32_16x16x32_bf16 v[48:51], v[140:143], v[156:159], v[48:51]
	v_mfma_f32_16x16x32_bf16 v[44:47], v[64:67], v[160:163], 0
	v_mfma_f32_16x16x32_bf16 v[44:47], v[72:75], v[164:167], v[44:47]
	v_mfma_f32_16x16x32_bf16 v[36:39], v[108:111], v[160:163], 0
	v_mfma_f32_16x16x32_bf16 v[36:39], v[116:119], v[164:167], v[36:39]
	v_mfma_f32_16x16x32_bf16 v[40:43], v[88:91], v[160:163], 0
	v_mfma_f32_16x16x32_bf16 v[40:43], v[96:99], v[164:167], v[40:43]
	v_mfma_f32_16x16x32_bf16 v[32:35], v[128:131], v[160:163], 0
	v_mfma_f32_16x16x32_bf16 v[32:35], v[140:143], v[164:167], v[32:35]
	v_mfma_f32_16x16x32_bf16 v[28:31], v[64:67], v[168:171], 0
	v_mfma_f32_16x16x32_bf16 v[28:31], v[72:75], v[180:183], v[28:31]
	v_mfma_f32_16x16x32_bf16 v[20:23], v[108:111], v[168:171], 0
	v_mfma_f32_16x16x32_bf16 v[20:23], v[116:119], v[180:183], v[20:23]
	v_mfma_f32_16x16x32_bf16 v[24:27], v[88:91], v[168:171], 0
	v_mfma_f32_16x16x32_bf16 v[24:27], v[96:99], v[180:183], v[24:27]
	v_mfma_f32_16x16x32_bf16 v[16:19], v[128:131], v[168:171], 0
	v_mfma_f32_16x16x32_bf16 v[16:19], v[140:143], v[180:183], v[16:19]
	v_mfma_f32_16x16x32_bf16 v[12:15], v[64:67], v[184:187], 0
	v_mfma_f32_16x16x32_bf16 v[12:15], v[72:75], v[188:191], v[12:15]
	v_mfma_f32_16x16x32_bf16 v[4:7], v[108:111], v[184:187], 0
	v_mfma_f32_16x16x32_bf16 v[4:7], v[116:119], v[188:191], v[4:7]
	v_mfma_f32_16x16x32_bf16 v[8:11], v[88:91], v[184:187], 0
	v_mfma_f32_16x16x32_bf16 v[8:11], v[96:99], v[188:191], v[8:11]
	v_mfma_f32_16x16x32_bf16 v[0:3], v[128:131], v[184:187], 0
	v_mfma_f32_16x16x32_bf16 v[0:3], v[140:143], v[188:191], v[0:3]
	s_barrier
	s_add_i32 s67, 0, 0x18000
	s_add_i32 s76, 0, 0x1c000
	ds_read_b128 v[64:67], v192 offset:32768
	ds_read_b128 v[72:75], v192 offset:33792
	ds_read_b128 v[88:91], v192 offset:34816
	ds_read_b128 v[96:99], v192 offset:35840
	ds_read_b128 v[108:111], v192 offset:49152
	ds_read_b128 v[116:119], v192 offset:50176
	ds_read_b128 v[128:131], v192 offset:51200
	ds_read_b128 v[140:143], v192 offset:52224
	s_add_u32 s2, s94, 0x80000
	s_addc_u32 s3, s95, 0
	s_mov_b32 m0, s55
	ds_read_b128 v[152:155], v240 offset:32768
	ds_read_b128 v[156:159], v240 offset:33792
	ds_read_b128 v[160:163], v240 offset:34816
	ds_read_b128 v[164:167], v240 offset:35840
	ds_read_b128 v[168:171], v240 offset:36864
	ds_read_b128 v[180:183], v240 offset:37888
	ds_read_b128 v[184:187], v240 offset:38912
	ds_read_b128 v[188:191], v240 offset:39936
	global_load_lds_dwordx4 v224, s[2:3]
	s_mov_b32 m0, s56
	s_nop 0
	global_load_lds_dwordx4 v226, s[2:3]
	s_waitcnt vmcnt(8)
	s_waitcnt lgkmcnt(0)
	s_barrier
	s_waitcnt lgkmcnt(0)
	v_mfma_f32_16x16x32_bf16 v[176:179], v[64:67], v[152:155], v[176:179]
	v_mfma_f32_16x16x32_bf16 v[176:179], v[72:75], v[156:159], v[176:179]
	v_mfma_f32_16x16x32_bf16 v[148:151], v[108:111], v[152:155], v[148:151]
	v_mfma_f32_16x16x32_bf16 v[148:151], v[116:119], v[156:159], v[148:151]
	v_mfma_f32_16x16x32_bf16 v[172:175], v[88:91], v[152:155], v[172:175]
	v_mfma_f32_16x16x32_bf16 v[172:175], v[96:99], v[156:159], v[172:175]
	v_mfma_f32_16x16x32_bf16 v[144:147], v[128:131], v[152:155], v[144:147]
	v_mfma_f32_16x16x32_bf16 v[144:147], v[140:143], v[156:159], v[144:147]
	v_mfma_f32_16x16x32_bf16 v[136:139], v[64:67], v[160:163], v[136:139]
	v_mfma_f32_16x16x32_bf16 v[136:139], v[72:75], v[164:167], v[136:139]
	v_mfma_f32_16x16x32_bf16 v[124:127], v[108:111], v[160:163], v[124:127]
	v_mfma_f32_16x16x32_bf16 v[124:127], v[116:119], v[164:167], v[124:127]
	v_mfma_f32_16x16x32_bf16 v[132:135], v[88:91], v[160:163], v[132:135]
	v_mfma_f32_16x16x32_bf16 v[132:135], v[96:99], v[164:167], v[132:135]
	v_mfma_f32_16x16x32_bf16 v[120:123], v[128:131], v[160:163], v[120:123]
	v_mfma_f32_16x16x32_bf16 v[120:123], v[140:143], v[164:167], v[120:123]
	v_mfma_f32_16x16x32_bf16 v[112:115], v[64:67], v[168:171], v[112:115]
	v_mfma_f32_16x16x32_bf16 v[112:115], v[72:75], v[180:183], v[112:115]
	v_mfma_f32_16x16x32_bf16 v[100:103], v[108:111], v[168:171], v[100:103]
	v_mfma_f32_16x16x32_bf16 v[100:103], v[116:119], v[180:183], v[100:103]
	v_mfma_f32_16x16x32_bf16 v[104:107], v[88:91], v[168:171], v[104:107]
	v_mfma_f32_16x16x32_bf16 v[104:107], v[96:99], v[180:183], v[104:107]
	v_mfma_f32_16x16x32_bf16 v[92:95], v[128:131], v[168:171], v[92:95]
	v_mfma_f32_16x16x32_bf16 v[92:95], v[140:143], v[180:183], v[92:95]
	v_mfma_f32_16x16x32_bf16 v[84:87], v[64:67], v[184:187], v[84:87]
	v_mfma_f32_16x16x32_bf16 v[84:87], v[72:75], v[188:191], v[84:87]
	v_mfma_f32_16x16x32_bf16 v[76:79], v[108:111], v[184:187], v[76:79]
	v_mfma_f32_16x16x32_bf16 v[76:79], v[116:119], v[188:191], v[76:79]
	v_mfma_f32_16x16x32_bf16 v[80:83], v[88:91], v[184:187], v[80:83]
	v_mfma_f32_16x16x32_bf16 v[80:83], v[96:99], v[188:191], v[80:83]
	v_mfma_f32_16x16x32_bf16 v[68:71], v[128:131], v[184:187], v[68:71]
	v_mfma_f32_16x16x32_bf16 v[68:71], v[140:143], v[188:191], v[68:71]
	s_barrier
	s_add_i32 s2, s67, s28
	s_add_u32 s98, s92, 0x80
	s_addc_u32 s99, s93, 0
	s_mov_b32 m0, s2
	ds_read_b128 v[152:155], v240 offset:49152
	ds_read_b128 v[156:159], v240 offset:50176
	ds_read_b128 v[160:163], v240 offset:51200
	ds_read_b128 v[164:167], v240 offset:52224
	ds_read_b128 v[168:171], v240 offset:53248
	ds_read_b128 v[180:183], v240 offset:54272
	ds_read_b128 v[184:187], v240 offset:55296
	ds_read_b128 v[188:191], v240 offset:56320
	global_load_lds_dwordx4 v216, s[98:99]
	s_add_i32 m0, s2, 0x2000
	s_add_u32 s2, s92, 0x80080
	s_addc_u32 s3, s93, 0
	s_add_i32 s67, s76, s28
	global_load_lds_dwordx4 v228, s[98:99]
	s_mov_b32 m0, s67
	s_nop 0
	global_load_lds_dwordx4 v216, s[2:3]
	s_add_i32 m0, s67, 0x2000
	s_nop 0
	global_load_lds_dwordx4 v228, s[2:3]
	s_add_u32 s98, s94, 0x80
	s_addc_u32 s99, s95, 0
	s_mov_b32 m0, s70
	s_nop 0
	global_load_lds_dwordx4 v224, s[98:99]
	s_mov_b32 m0, s71
	s_nop 0
	global_load_lds_dwordx4 v226, s[98:99]
	s_waitcnt vmcnt(8)
	s_waitcnt lgkmcnt(0)
	s_barrier
	s_waitcnt lgkmcnt(0)
	v_mfma_f32_16x16x32_bf16 v[60:63], v[64:67], v[152:155], v[60:63]
	v_mfma_f32_16x16x32_bf16 v[60:63], v[72:75], v[156:159], v[60:63]
	v_mfma_f32_16x16x32_bf16 v[52:55], v[108:111], v[152:155], v[52:55]
	v_mfma_f32_16x16x32_bf16 v[52:55], v[116:119], v[156:159], v[52:55]
	v_mfma_f32_16x16x32_bf16 v[56:59], v[88:91], v[152:155], v[56:59]
	v_mfma_f32_16x16x32_bf16 v[56:59], v[96:99], v[156:159], v[56:59]
	v_mfma_f32_16x16x32_bf16 v[48:51], v[128:131], v[152:155], v[48:51]
	v_mfma_f32_16x16x32_bf16 v[48:51], v[140:143], v[156:159], v[48:51]
	v_mfma_f32_16x16x32_bf16 v[44:47], v[64:67], v[160:163], v[44:47]
	v_mfma_f32_16x16x32_bf16 v[44:47], v[72:75], v[164:167], v[44:47]
	v_mfma_f32_16x16x32_bf16 v[36:39], v[108:111], v[160:163], v[36:39]
	v_mfma_f32_16x16x32_bf16 v[36:39], v[116:119], v[164:167], v[36:39]
	v_mfma_f32_16x16x32_bf16 v[40:43], v[88:91], v[160:163], v[40:43]
	v_mfma_f32_16x16x32_bf16 v[40:43], v[96:99], v[164:167], v[40:43]
	v_mfma_f32_16x16x32_bf16 v[32:35], v[128:131], v[160:163], v[32:35]
	v_mfma_f32_16x16x32_bf16 v[32:35], v[140:143], v[164:167], v[32:35]
	v_mfma_f32_16x16x32_bf16 v[28:31], v[64:67], v[168:171], v[28:31]
	v_mfma_f32_16x16x32_bf16 v[28:31], v[72:75], v[180:183], v[28:31]
	v_mfma_f32_16x16x32_bf16 v[20:23], v[108:111], v[168:171], v[20:23]
	v_mfma_f32_16x16x32_bf16 v[20:23], v[116:119], v[180:183], v[20:23]
	v_mfma_f32_16x16x32_bf16 v[24:27], v[88:91], v[168:171], v[24:27]
	v_mfma_f32_16x16x32_bf16 v[24:27], v[96:99], v[180:183], v[24:27]
	v_mfma_f32_16x16x32_bf16 v[16:19], v[128:131], v[168:171], v[16:19]
	v_mfma_f32_16x16x32_bf16 v[16:19], v[140:143], v[180:183], v[16:19]
	v_mfma_f32_16x16x32_bf16 v[12:15], v[64:67], v[184:187], v[12:15]
	v_mfma_f32_16x16x32_bf16 v[12:15], v[72:75], v[188:191], v[12:15]
	v_mfma_f32_16x16x32_bf16 v[4:7], v[108:111], v[184:187], v[4:7]
	v_mfma_f32_16x16x32_bf16 v[4:7], v[116:119], v[188:191], v[4:7]
	v_mfma_f32_16x16x32_bf16 v[8:11], v[88:91], v[184:187], v[8:11]
	v_mfma_f32_16x16x32_bf16 v[8:11], v[96:99], v[188:191], v[8:11]
	v_mfma_f32_16x16x32_bf16 v[0:3], v[128:131], v[184:187], v[0:3]
	v_mfma_f32_16x16x32_bf16 v[0:3], v[140:143], v[188:191], v[0:3]
	s_barrier
	s_add_i32 s20, s20, 2
	s_add_u32 s90, s90, 0x100
	s_addc_u32 s91, s91, 0
	s_add_u32 s89, s89, 0x100
	s_addc_u32 s14, s14, 0

.LBB0_628:
	v_add_u32_e32 v177, 0x10000, v194
	ds_read_b128 v[40:43], v177
	ds_read_b128 v[44:47], v177 offset:1024
	ds_read_b128 v[48:51], v177 offset:2048
	ds_read_b128 v[52:55], v177 offset:3072
	ds_read_b128 v[64:67], v177 offset:16384
	ds_read_b128 v[100:103], v177 offset:17408
	ds_read_b128 v[120:123], v177 offset:18432
	ds_read_b128 v[124:127], v177 offset:19456
	ds_read_b128 v[136:139], v195
	ds_read_b128 v[140:143], v195 offset:1024
	ds_read_b128 v[144:147], v195 offset:2048
	ds_read_b128 v[172:175], v195 offset:3072
	ds_read_b128 v[190:193], v195 offset:4096
	ds_read_b128 v[196:199], v195 offset:5120
	ds_read_b128 v[200:203], v195 offset:6144
	ds_read_b128 v[204:207], v195 offset:7168
	s_add_i32 s39, s3, 1
	s_mul_i32 s4, s39, s60
	s_mul_hi_u32 s5, s39, s0
	s_add_i32 s5, s5, s4
	s_mul_i32 s4, s39, s0
	s_add_u32 s88, s4, s1
	s_addc_u32 s89, s5, s38
	v_cmp_gt_i64_e32 vcc, s[88:89], v[228:229]
	v_cmp_lt_i64_e64 s[4:5], s[88:89], v[220:221]
	s_cbranch_vccnz .LBB0_630
	s_ashr_i32 s7, s88, 31
	s_lshr_b32 s7, s7, 29
	s_add_i32 s7, s88, s7
	s_ashr_i32 s9, s7, 3
	s_and_b32 s7, s7, -8
	s_sub_i32 s7, s88, s7
	s_cmp_lt_i32 s7, 0
	s_movk_i32 s40, 0x111
	s_cselect_b32 s40, s40, 0x110
	s_mul_i32 s7, s7, s40
	s_add_i32 s7, s7, s9
	s_ashr_i32 s9, s7, 31
	s_lshr_b32 s9, s9, 26
	s_add_i32 s9, s7, s9
	s_ashr_i32 s40, s9, 6
	s_lshl_b32 s40, s40, 2
	s_sub_i32 s41, 0x88, s40
	s_min_i32 s41, s41, 4
	s_abs_i32 s54, s41
	v_cvt_f32_u32_e32 v0, s54
	s_sub_i32 s67, 0, s54
	s_andn2_b32 s9, s9, 63
	s_sub_i32 s7, s7, s9
	v_rcp_iflag_f32_e32 v0, v0
	s_abs_i32 s9, s7
	s_xor_b32 s55, s7, s41
	s_ashr_i32 s55, s55, 31
	v_mul_f32_e32 v0, 0x4f7ffffe, v0
	v_cvt_u32_f32_e32 v0, v0
	s_nop 0
	v_readfirstlane_b32 s84, v0
	s_mul_i32 s67, s67, s84
	s_mul_hi_u32 s67, s84, s67
	s_add_i32 s84, s84, s67
	s_mul_hi_u32 s67, s9, s84
	s_mul_i32 s84, s67, s54
	s_sub_i32 s9, s9, s84
	s_add_i32 s85, s67, 1
	s_sub_i32 s84, s9, s54
	s_cmp_ge_u32 s9, s54
	s_cselect_b32 s67, s85, s67
	s_cselect_b32 s9, s84, s9
	s_add_i32 s84, s67, 1
	s_cmp_ge_u32 s9, s54
	s_cselect_b32 s9, s84, s67
	s_xor_b32 s9, s9, s55
	s_sub_i32 s84, s9, s55
	s_mul_i32 s9, s84, s41
	s_sub_i32 s7, s7, s9
	s_add_i32 s86, s40, s7

.LBB0_638:
	s_ashr_i32 s87, s86, 31
	s_lshl_b64 s[40:41], s[86:87], 20
	s_add_u32 s88, s14, s40
	s_addc_u32 s89, s15, s41
	s_and_b64 s[40:41], s[4:5], exec
	s_cselect_b32 s7, s89, s11
	s_cselect_b32 s9, s88, s10
	s_ashr_i32 s85, s84, 31
	s_lshl_b64 s[40:41], s[84:85], 20
	s_add_u32 s90, s24, s40
	s_addc_u32 s91, s26, s41
	s_and_b64 s[40:41], s[4:5], exec
	s_cselect_b32 s40, s91, s93
	s_cselect_b32 s41, s90, s92
	s_add_u32 s10, s10, 0x80080
	s_addc_u32 s11, s11, 0
	s_add_u32 s54, s92, 0x100
	s_addc_u32 s55, s93, 0
	s_mov_b32 s85, -2
	s_add_u32 s67, s10, 0xfff80080
	s_addc_u32 s87, s11, -1
	s_add_i32 s96, 0, 0x10000
	s_cmp_eq_u32 s85, 28
	s_cselect_b32 s95, s7, s87
	s_cselect_b32 s94, s9, s67
	s_cselect_b32 s93, s40, s55
	s_cselect_b32 s92, s41, s54
	s_add_i32 s67, 0, 0x14000
	s_add_i32 m0, s57, 0xc000
	global_load_lds_dwordx4 v186, s[10:11]
	s_add_i32 m0, s57, 0xe000
	s_nop 0
	global_load_lds_dwordx4 v188, s[10:11]
	s_waitcnt vmcnt(8)
	s_waitcnt lgkmcnt(0)
	s_barrier
	s_waitcnt lgkmcnt(0)
	v_mfma_f32_16x16x32_bf16 v[168:171], v[40:43], v[136:139], 0
	v_mfma_f32_16x16x32_bf16 v[168:171], v[44:47], v[140:143], v[168:171]
	v_mfma_f32_16x16x32_bf16 v[160:163], v[64:67], v[136:139], 0
	v_mfma_f32_16x16x32_bf16 v[160:163], v[100:103], v[140:143], v[160:163]
	v_mfma_f32_16x16x32_bf16 v[164:167], v[48:51], v[136:139], 0
	v_mfma_f32_16x16x32_bf16 v[164:167], v[52:55], v[140:143], v[164:167]
	v_mfma_f32_16x16x32_bf16 v[132:135], v[64:67], v[144:147], 0
	v_mfma_f32_16x16x32_bf16 v[132:135], v[100:103], v[172:175], v[132:135]
	v_mfma_f32_16x16x32_bf16 v[152:155], v[40:43], v[144:147], 0
	v_mfma_f32_16x16x32_bf16 v[152:155], v[44:47], v[172:175], v[152:155]
	v_mfma_f32_16x16x32_bf16 v[128:131], v[120:123], v[144:147], 0
	v_mfma_f32_16x16x32_bf16 v[128:131], v[124:127], v[172:175], v[128:131]
	v_mfma_f32_16x16x32_bf16 v[148:151], v[48:51], v[144:147], 0
	v_mfma_f32_16x16x32_bf16 v[148:151], v[52:55], v[172:175], v[148:151]
	v_mfma_f32_16x16x32_bf16 v[108:111], v[64:67], v[190:193], 0
	v_mfma_f32_16x16x32_bf16 v[108:111], v[100:103], v[196:199], v[108:111]
	v_mfma_f32_16x16x32_bf16 v[116:119], v[40:43], v[190:193], 0
	v_mfma_f32_16x16x32_bf16 v[116:119], v[44:47], v[196:199], v[116:119]
	v_mfma_f32_16x16x32_bf16 v[104:107], v[120:123], v[190:193], 0
	v_mfma_f32_16x16x32_bf16 v[104:107], v[124:127], v[196:199], v[104:107]
	v_mfma_f32_16x16x32_bf16 v[112:115], v[48:51], v[190:193], 0
	v_mfma_f32_16x16x32_bf16 v[112:115], v[52:55], v[196:199], v[112:115]
	v_mfma_f32_16x16x32_bf16 v[88:91], v[64:67], v[200:203], 0
	v_mfma_f32_16x16x32_bf16 v[88:91], v[100:103], v[204:207], v[88:91]
	v_mfma_f32_16x16x32_bf16 v[96:99], v[40:43], v[200:203], 0
	v_mfma_f32_16x16x32_bf16 v[96:99], v[44:47], v[204:207], v[96:99]
	v_mfma_f32_16x16x32_bf16 v[84:87], v[120:123], v[200:203], 0
	v_mfma_f32_16x16x32_bf16 v[84:87], v[124:127], v[204:207], v[84:87]
	v_mfma_f32_16x16x32_bf16 v[92:95], v[48:51], v[200:203], 0
	v_mfma_f32_16x16x32_bf16 v[92:95], v[52:55], v[204:207], v[92:95]
	v_mfma_f32_16x16x32_bf16 v[136:139], v[120:123], v[136:139], 0
	v_mfma_f32_16x16x32_bf16 v[136:139], v[124:127], v[140:143], v[136:139]
	s_barrier
	s_add_i32 s87, s96, s56
	s_mov_b32 m0, s87
	ds_read_b128 v[140:143], v195 offset:16384
	ds_read_b128 v[144:147], v195 offset:17408
	ds_read_b128 v[156:159], v195 offset:18432
	ds_read_b128 v[172:175], v195 offset:19456
	ds_read_b128 v[190:193], v195 offset:20480
	ds_read_b128 v[196:199], v195 offset:21504
	ds_read_b128 v[200:203], v195 offset:22528
	ds_read_b128 v[204:207], v195 offset:23552
	global_load_lds_dwordx4 v178, s[92:93]
	s_add_i32 m0, s87, 0x2000
	s_add_u32 vcc_lo, s92, 0x80000
	s_addc_u32 vcc_hi, s93, 0
	s_add_i32 s67, s67, s56
	global_load_lds_dwordx4 v182, s[92:93]
	v_lshl_add_u64 v[208:209], vcc, 0, v[178:179]
	s_mov_b32 m0, s67
	s_nop 0
	global_load_lds_dwordx4 v[208:209], off
	v_lshl_add_u64 v[208:209], vcc, 0, v[182:183]
	s_add_i32 m0, s67, 0x2000
	s_nop 0
	global_load_lds_dwordx4 v[208:209], off
	s_mov_b32 m0, s57
	s_nop 0
	global_load_lds_dwordx4 v176, s[94:95]
	s_mov_b32 m0, s61
	s_nop 0
	global_load_lds_dwordx4 v180, s[94:95]
	s_waitcnt vmcnt(8)
	s_waitcnt lgkmcnt(0)
	s_barrier
	s_waitcnt lgkmcnt(0)
	v_mfma_f32_16x16x32_bf16 v[80:83], v[40:43], v[140:143], 0
	v_mfma_f32_16x16x32_bf16 v[80:83], v[44:47], v[144:147], v[80:83]
	v_mfma_f32_16x16x32_bf16 v[36:39], v[64:67], v[156:159], 0
	v_mfma_f32_16x16x32_bf16 v[36:39], v[100:103], v[172:175], v[36:39]
	v_mfma_f32_16x16x32_bf16 v[76:79], v[48:51], v[140:143], 0
	v_mfma_f32_16x16x32_bf16 v[76:79], v[52:55], v[144:147], v[76:79]
	v_mfma_f32_16x16x32_bf16 v[32:35], v[120:123], v[156:159], 0
	v_mfma_f32_16x16x32_bf16 v[32:35], v[124:127], v[172:175], v[32:35]
	v_mfma_f32_16x16x32_bf16 v[60:63], v[40:43], v[156:159], 0
	v_mfma_f32_16x16x32_bf16 v[60:63], v[44:47], v[172:175], v[60:63]
	v_mfma_f32_16x16x32_bf16 v[20:23], v[64:67], v[190:193], 0
	v_mfma_f32_16x16x32_bf16 v[20:23], v[100:103], v[196:199], v[20:23]
	v_mfma_f32_16x16x32_bf16 v[56:59], v[48:51], v[156:159], 0
	v_mfma_f32_16x16x32_bf16 v[56:59], v[52:55], v[172:175], v[56:59]
	v_mfma_f32_16x16x32_bf16 v[16:19], v[120:123], v[190:193], 0
	v_mfma_f32_16x16x32_bf16 v[16:19], v[124:127], v[196:199], v[16:19]
	v_mfma_f32_16x16x32_bf16 v[28:31], v[40:43], v[190:193], 0
	v_mfma_f32_16x16x32_bf16 v[28:31], v[44:47], v[196:199], v[28:31]
	v_mfma_f32_16x16x32_bf16 v[4:7], v[64:67], v[200:203], 0
	v_mfma_f32_16x16x32_bf16 v[4:7], v[100:103], v[204:207], v[4:7]
	v_mfma_f32_16x16x32_bf16 v[24:27], v[48:51], v[190:193], 0
	v_mfma_f32_16x16x32_bf16 v[24:27], v[52:55], v[196:199], v[24:27]
	v_mfma_f32_16x16x32_bf16 v[0:3], v[120:123], v[200:203], 0
	v_mfma_f32_16x16x32_bf16 v[0:3], v[124:127], v[204:207], v[0:3]
	v_mfma_f32_16x16x32_bf16 v[12:15], v[40:43], v[200:203], 0
	v_mfma_f32_16x16x32_bf16 v[12:15], v[44:47], v[204:207], v[12:15]
	v_mfma_f32_16x16x32_bf16 v[40:43], v[64:67], v[140:143], 0
	v_mfma_f32_16x16x32_bf16 v[40:43], v[100:103], v[144:147], v[40:43]
	v_mfma_f32_16x16x32_bf16 v[8:11], v[48:51], v[200:203], 0
	v_mfma_f32_16x16x32_bf16 v[8:11], v[52:55], v[204:207], v[8:11]
	v_mfma_f32_16x16x32_bf16 v[44:47], v[120:123], v[140:143], 0
	v_mfma_f32_16x16x32_bf16 v[44:47], v[124:127], v[144:147], v[44:47]
	s_barrier
	s_add_i32 s67, 0, 0x18000
	s_add_i32 s87, 0, 0x1c000
	ds_read_b128 v[48:51], v177 offset:32768
	ds_read_b128 v[52:55], v177 offset:33792
	ds_read_b128 v[64:67], v177 offset:34816
	ds_read_b128 v[68:71], v177 offset:35840
	ds_read_b128 v[100:103], v177 offset:49152
	ds_read_b128 v[120:123], v177 offset:50176
	ds_read_b128 v[124:127], v177 offset:51200
	ds_read_b128 v[140:143], v177 offset:52224
	s_add_u32 s94, s94, 0x80000
	s_addc_u32 s95, s95, 0
	s_mov_b32 m0, s68
	ds_read_b128 v[72:75], v195 offset:32768
	ds_read_b128 v[144:147], v195 offset:33792
	ds_read_b128 v[172:175], v195 offset:34816
	ds_read_b128 v[190:193], v195 offset:35840
	ds_read_b128 v[196:199], v195 offset:36864
	ds_read_b128 v[200:203], v195 offset:37888
	ds_read_b128 v[204:207], v195 offset:38912
	ds_read_b128 v[208:211], v195 offset:39936
	global_load_lds_dwordx4 v176, s[94:95]
	s_mov_b32 m0, s69
	s_nop 0
	global_load_lds_dwordx4 v180, s[94:95]
	s_waitcnt vmcnt(8)
	s_waitcnt lgkmcnt(0)
	s_barrier
	s_waitcnt lgkmcnt(0)
	v_mfma_f32_16x16x32_bf16 v[156:159], v[48:51], v[72:75], v[168:171]
	v_mfma_f32_16x16x32_bf16 v[168:171], v[52:55], v[144:147], v[156:159]
	v_mfma_f32_16x16x32_bf16 v[156:159], v[64:67], v[72:75], v[164:167]
	v_mfma_f32_16x16x32_bf16 v[164:167], v[68:71], v[144:147], v[156:159]
	v_mfma_f32_16x16x32_bf16 v[152:155], v[48:51], v[172:175], v[152:155]
	v_mfma_f32_16x16x32_bf16 v[152:155], v[52:55], v[190:193], v[152:155]
	v_mfma_f32_16x16x32_bf16 v[148:151], v[64:67], v[172:175], v[148:151]
	v_mfma_f32_16x16x32_bf16 v[148:151], v[68:71], v[190:193], v[148:151]
	v_mfma_f32_16x16x32_bf16 v[116:119], v[48:51], v[196:199], v[116:119]
	v_mfma_f32_16x16x32_bf16 v[116:119], v[52:55], v[200:203], v[116:119]
	v_mfma_f32_16x16x32_bf16 v[112:115], v[64:67], v[196:199], v[112:115]
	v_mfma_f32_16x16x32_bf16 v[112:115], v[68:71], v[200:203], v[112:115]
	v_mfma_f32_16x16x32_bf16 v[96:99], v[48:51], v[204:207], v[96:99]
	v_mfma_f32_16x16x32_bf16 v[96:99], v[52:55], v[208:211], v[96:99]
	v_mfma_f32_16x16x32_bf16 v[92:95], v[64:67], v[204:207], v[92:95]
	v_mfma_f32_16x16x32_bf16 v[92:95], v[68:71], v[208:211], v[92:95]
	v_mfma_f32_16x16x32_bf16 v[156:159], v[100:103], v[72:75], v[160:163]
	v_mfma_f32_16x16x32_bf16 v[160:163], v[120:123], v[144:147], v[156:159]
	v_mfma_f32_16x16x32_bf16 v[72:75], v[124:127], v[72:75], v[136:139]
	v_mfma_f32_16x16x32_bf16 v[156:159], v[140:143], v[144:147], v[72:75]
	v_mfma_f32_16x16x32_bf16 v[72:75], v[100:103], v[172:175], v[132:135]
	v_mfma_f32_16x16x32_bf16 v[132:135], v[120:123], v[190:193], v[72:75]
	v_mfma_f32_16x16x32_bf16 v[72:75], v[124:127], v[172:175], v[128:131]
	v_mfma_f32_16x16x32_bf16 v[128:131], v[140:143], v[190:193], v[72:75]
	v_mfma_f32_16x16x32_bf16 v[72:75], v[100:103], v[196:199], v[108:111]
	v_mfma_f32_16x16x32_bf16 v[108:111], v[120:123], v[200:203], v[72:75]
	v_mfma_f32_16x16x32_bf16 v[72:75], v[124:127], v[196:199], v[104:107]
	v_mfma_f32_16x16x32_bf16 v[104:107], v[140:143], v[200:203], v[72:75]
	v_mfma_f32_16x16x32_bf16 v[72:75], v[100:103], v[204:207], v[88:91]
	v_mfma_f32_16x16x32_bf16 v[88:91], v[120:123], v[208:211], v[72:75]
	v_mfma_f32_16x16x32_bf16 v[72:75], v[124:127], v[204:207], v[84:87]
	v_mfma_f32_16x16x32_bf16 v[84:87], v[140:143], v[208:211], v[72:75]
	s_barrier
	s_add_i32 s67, s67, s56
	s_nop 3
	s_add_u32 s98, s92, 0x80
	s_addc_u32 s99, s93, 0
	s_mov_b32 m0, s67
	ds_read_b128 v[136:139], v195 offset:49152
	ds_read_b128 v[144:147], v195 offset:50176
	ds_read_b128 v[172:175], v195 offset:51200
	ds_read_b128 v[190:193], v195 offset:52224
	ds_read_b128 v[196:199], v195 offset:53248
	ds_read_b128 v[200:203], v195 offset:54272
	ds_read_b128 v[204:207], v195 offset:55296
	ds_read_b128 v[208:211], v195 offset:56320
	global_load_lds_dwordx4 v178, s[98:99]
	s_add_i32 m0, s67, 0x2000
	s_add_u32 s92, s92, 0x80080
	s_addc_u32 s93, s93, 0
	s_add_i32 s67, s87, s56
	global_load_lds_dwordx4 v182, s[98:99]
	s_mov_b32 m0, s67
	s_nop 0
	global_load_lds_dwordx4 v178, s[92:93]
	s_add_i32 m0, s67, 0x2000
	s_nop 0
	global_load_lds_dwordx4 v182, s[92:93]
	s_add_u32 s98, s94, 0xfff80080
	s_addc_u32 s99, s95, -1
	s_mov_b32 m0, s2
	s_nop 0
	global_load_lds_dwordx4 v176, s[98:99]
	s_mov_b32 m0, s28
	s_nop 0
	global_load_lds_dwordx4 v180, s[98:99]
	s_waitcnt vmcnt(8)
	s_waitcnt lgkmcnt(0)
	s_barrier
	s_waitcnt lgkmcnt(0)
	v_mfma_f32_16x16x32_bf16 v[72:75], v[48:51], v[136:139], v[80:83]
	v_mfma_f32_16x16x32_bf16 v[80:83], v[52:55], v[144:147], v[72:75]
	v_mfma_f32_16x16x32_bf16 v[72:75], v[64:67], v[136:139], v[76:79]
	v_mfma_f32_16x16x32_bf16 v[76:79], v[68:71], v[144:147], v[72:75]
	v_mfma_f32_16x16x32_bf16 v[60:63], v[48:51], v[172:175], v[60:63]
	v_mfma_f32_16x16x32_bf16 v[60:63], v[52:55], v[190:193], v[60:63]
	v_mfma_f32_16x16x32_bf16 v[56:59], v[64:67], v[172:175], v[56:59]
	v_mfma_f32_16x16x32_bf16 v[56:59], v[68:71], v[190:193], v[56:59]
	v_mfma_f32_16x16x32_bf16 v[28:31], v[48:51], v[196:199], v[28:31]
	v_mfma_f32_16x16x32_bf16 v[28:31], v[52:55], v[200:203], v[28:31]
	v_mfma_f32_16x16x32_bf16 v[24:27], v[64:67], v[196:199], v[24:27]
	v_mfma_f32_16x16x32_bf16 v[24:27], v[68:71], v[200:203], v[24:27]
	v_mfma_f32_16x16x32_bf16 v[12:15], v[48:51], v[204:207], v[12:15]
	v_mfma_f32_16x16x32_bf16 v[12:15], v[52:55], v[208:211], v[12:15]
	v_mfma_f32_16x16x32_bf16 v[8:11], v[64:67], v[204:207], v[8:11]
	v_mfma_f32_16x16x32_bf16 v[8:11], v[68:71], v[208:211], v[8:11]
	v_mfma_f32_16x16x32_bf16 v[40:43], v[100:103], v[136:139], v[40:43]
	v_mfma_f32_16x16x32_bf16 v[72:75], v[120:123], v[144:147], v[40:43]
	v_mfma_f32_16x16x32_bf16 v[40:43], v[124:127], v[136:139], v[44:47]
	v_mfma_f32_16x16x32_bf16 v[68:71], v[140:143], v[144:147], v[40:43]
	v_mfma_f32_16x16x32_bf16 v[36:39], v[100:103], v[172:175], v[36:39]
	v_mfma_f32_16x16x32_bf16 v[36:39], v[120:123], v[190:193], v[36:39]
	v_mfma_f32_16x16x32_bf16 v[32:35], v[124:127], v[172:175], v[32:35]
	v_mfma_f32_16x16x32_bf16 v[32:35], v[140:143], v[190:193], v[32:35]
	v_mfma_f32_16x16x32_bf16 v[20:23], v[100:103], v[196:199], v[20:23]
	v_mfma_f32_16x16x32_bf16 v[20:23], v[120:123], v[200:203], v[20:23]
	v_mfma_f32_16x16x32_bf16 v[16:19], v[124:127], v[196:199], v[16:19]
	v_mfma_f32_16x16x32_bf16 v[16:19], v[140:143], v[200:203], v[16:19]
	v_mfma_f32_16x16x32_bf16 v[4:7], v[100:103], v[204:207], v[4:7]
	v_mfma_f32_16x16x32_bf16 v[4:7], v[120:123], v[208:211], v[4:7]
	v_mfma_f32_16x16x32_bf16 v[0:3], v[124:127], v[204:207], v[0:3]
	v_mfma_f32_16x16x32_bf16 v[0:3], v[140:143], v[208:211], v[0:3]
	s_barrier
	s_add_i32 s85, s85, 2
	s_add_u32 s10, s10, 0x100
	s_addc_u32 s11, s11, 0
	s_add_u32 s54, s54, 0x100
	s_addc_u32 s55, s55, 0

.LBB0_950:
	v_add_u32_e32 v192, 0x10000, v238
	ds_read_b128 v[64:67], v192
	ds_read_b128 v[72:75], v192 offset:1024
	ds_read_b128 v[88:91], v192 offset:2048
	ds_read_b128 v[96:99], v192 offset:3072
	ds_read_b128 v[108:111], v192 offset:16384
	ds_read_b128 v[116:119], v192 offset:17408
	ds_read_b128 v[128:131], v192 offset:18432
	ds_read_b128 v[140:143], v192 offset:19456
	ds_read_b128 v[152:155], v240
	ds_read_b128 v[156:159], v240 offset:1024
	ds_read_b128 v[160:163], v240 offset:2048
	ds_read_b128 v[164:167], v240 offset:3072
	ds_read_b128 v[168:171], v240 offset:4096
	ds_read_b128 v[180:183], v240 offset:5120
	ds_read_b128 v[184:187], v240 offset:6144
	ds_read_b128 v[188:191], v240 offset:7168
	s_mov_b64 s[82:83], 0
	s_andn2_b64 vcc, exec, s[8:9]
	s_mov_b64 s[80:81], 0
	s_mov_b64 s[84:85], s[10:11]
	s_cbranch_vccz .LBB0_952
	s_andn2_b64 vcc, exec, s[84:85]
	s_add_i32 s94, s54, 1
	s_cbranch_vccz .LBB0_953
	s_branch .LBB0_955

.LBB0_964:
	s_ashr_i32 s79, s78, 31
	s_lshl_b64 s[82:83], s[78:79], 20
	s_add_u32 s82, s14, s82
	s_addc_u32 s83, s15, s83
	s_and_b64 s[84:85], s[80:81], exec
	s_cselect_b32 s79, s83, s93
	s_cselect_b32 s96, s82, s92
	s_ashr_i32 s77, s76, 31
	s_lshl_b64 s[84:85], s[76:77], 20
	s_add_u32 s84, s24, s84
	s_addc_u32 s85, s26, s85
	s_and_b64 vcc, s[80:81], exec
	s_cselect_b32 s77, s85, s91
	s_cselect_b32 vcc_lo, s84, s90
	s_lshl_b32 s86, s86, 8
	s_ashr_i32 s87, s86, 31
	s_lshl_b64 s[74:75], s[86:87], 2
	s_add_u32 s74, s88, s74
	s_addc_u32 s75, s89, s75
	s_add_i32 m0, s71, s40
	s_add_u32 s88, s92, 0x80080
	global_load_lds_dwordx4 v239, s[74:75]
	s_addc_u32 s89, s93, 0
	s_add_u32 s87, s90, 0x100
	s_addc_u32 vcc_hi, s91, 0
	s_mov_b32 s71, -2
	s_waitcnt vmcnt(0)
	s_add_u32 s67, s88, 0xfff80080
	s_addc_u32 s74, s89, -1
	s_add_i32 s75, 0, 0x10000
	s_cmp_eq_u32 s71, 28
	s_cselect_b32 s93, s79, s74
	s_cselect_b32 s92, s96, s67
	s_cselect_b32 s91, s77, vcc_hi
	s_cselect_b32 s90, vcc_lo, s87
	s_add_i32 s67, 0, 0x14000
	s_add_i32 m0, s28, 0xc000
	global_load_lds_dwordx4 v230, s[88:89]
	s_add_i32 m0, s28, 0xe000
	s_nop 0
	global_load_lds_dwordx4 v232, s[88:89]
	s_waitcnt vmcnt(8)
	s_waitcnt lgkmcnt(0)
	s_barrier
	s_waitcnt lgkmcnt(0)
	v_mfma_f32_16x16x32_bf16 v[176:179], v[64:67], v[152:155], 0
	v_mfma_f32_16x16x32_bf16 v[176:179], v[72:75], v[156:159], v[176:179]
	v_mfma_f32_16x16x32_bf16 v[148:151], v[108:111], v[152:155], 0
	v_mfma_f32_16x16x32_bf16 v[148:151], v[116:119], v[156:159], v[148:151]
	v_mfma_f32_16x16x32_bf16 v[172:175], v[88:91], v[152:155], 0
	v_mfma_f32_16x16x32_bf16 v[172:175], v[96:99], v[156:159], v[172:175]
	v_mfma_f32_16x16x32_bf16 v[144:147], v[128:131], v[152:155], 0
	v_mfma_f32_16x16x32_bf16 v[144:147], v[140:143], v[156:159], v[144:147]
	v_mfma_f32_16x16x32_bf16 v[136:139], v[64:67], v[160:163], 0
	v_mfma_f32_16x16x32_bf16 v[136:139], v[72:75], v[164:167], v[136:139]
	v_mfma_f32_16x16x32_bf16 v[124:127], v[108:111], v[160:163], 0
	v_mfma_f32_16x16x32_bf16 v[124:127], v[116:119], v[164:167], v[124:127]
	v_mfma_f32_16x16x32_bf16 v[132:135], v[88:91], v[160:163], 0
	v_mfma_f32_16x16x32_bf16 v[132:135], v[96:99], v[164:167], v[132:135]
	v_mfma_f32_16x16x32_bf16 v[120:123], v[128:131], v[160:163], 0
	v_mfma_f32_16x16x32_bf16 v[120:123], v[140:143], v[164:167], v[120:123]
	v_mfma_f32_16x16x32_bf16 v[112:115], v[64:67], v[168:171], 0
	v_mfma_f32_16x16x32_bf16 v[112:115], v[72:75], v[180:183], v[112:115]
	v_mfma_f32_16x16x32_bf16 v[100:103], v[108:111], v[168:171], 0
	v_mfma_f32_16x16x32_bf16 v[100:103], v[116:119], v[180:183], v[100:103]
	v_mfma_f32_16x16x32_bf16 v[104:107], v[88:91], v[168:171], 0
	v_mfma_f32_16x16x32_bf16 v[104:107], v[96:99], v[180:183], v[104:107]
	v_mfma_f32_16x16x32_bf16 v[92:95], v[128:131], v[168:171], 0
	v_mfma_f32_16x16x32_bf16 v[92:95], v[140:143], v[180:183], v[92:95]
	v_mfma_f32_16x16x32_bf16 v[84:87], v[64:67], v[184:187], 0
	v_mfma_f32_16x16x32_bf16 v[84:87], v[72:75], v[188:191], v[84:87]
	v_mfma_f32_16x16x32_bf16 v[76:79], v[108:111], v[184:187], 0
	v_mfma_f32_16x16x32_bf16 v[76:79], v[116:119], v[188:191], v[76:79]
	v_mfma_f32_16x16x32_bf16 v[80:83], v[88:91], v[184:187], 0
	v_mfma_f32_16x16x32_bf16 v[80:83], v[96:99], v[188:191], v[80:83]
	v_mfma_f32_16x16x32_bf16 v[68:71], v[128:131], v[184:187], 0
	v_mfma_f32_16x16x32_bf16 v[68:71], v[140:143], v[188:191], v[68:71]
	s_barrier
	s_add_i32 s74, s75, s2
	s_mov_b32 m0, s74
	ds_read_b128 v[152:155], v240 offset:16384
	ds_read_b128 v[156:159], v240 offset:17408
	ds_read_b128 v[160:163], v240 offset:18432
	ds_read_b128 v[164:167], v240 offset:19456
	ds_read_b128 v[168:171], v240 offset:20480
	ds_read_b128 v[180:183], v240 offset:21504
	ds_read_b128 v[184:187], v240 offset:22528
	ds_read_b128 v[188:191], v240 offset:23552
	global_load_lds_dwordx4 v216, s[90:91]
	s_add_i32 m0, s74, 0x2000
	s_add_u32 s74, s90, 0x80000
	s_addc_u32 s75, s91, 0
	s_add_i32 s67, s67, s2
	global_load_lds_dwordx4 v228, s[90:91]
	s_mov_b32 m0, s67
	s_nop 0
	global_load_lds_dwordx4 v216, s[74:75]
	s_add_i32 m0, s67, 0x2000
	s_nop 0
	global_load_lds_dwordx4 v228, s[74:75]
	s_mov_b32 m0, s28
	s_nop 0
	global_load_lds_dwordx4 v224, s[92:93]
	s_mov_b32 m0, s29
	s_nop 0
	global_load_lds_dwordx4 v226, s[92:93]
	s_waitcnt vmcnt(8)
	s_waitcnt lgkmcnt(0)
	s_barrier
	s_waitcnt lgkmcnt(0)
	v_mfma_f32_16x16x32_bf16 v[60:63], v[64:67], v[152:155], 0
	v_mfma_f32_16x16x32_bf16 v[60:63], v[72:75], v[156:159], v[60:63]
	v_mfma_f32_16x16x32_bf16 v[52:55], v[108:111], v[152:155], 0
	v_mfma_f32_16x16x32_bf16 v[52:55], v[116:119], v[156:159], v[52:55]
	v_mfma_f32_16x16x32_bf16 v[56:59], v[88:91], v[152:155], 0
	v_mfma_f32_16x16x32_bf16 v[56:59], v[96:99], v[156:159], v[56:59]
	v_mfma_f32_16x16x32_bf16 v[48:51], v[128:131], v[152:155], 0
	v_mfma_f32_16x16x32_bf16 v[48:51], v[140:143], v[156:159], v[48:51]
	v_mfma_f32_16x16x32_bf16 v[44:47], v[64:67], v[160:163], 0
	v_mfma_f32_16x16x32_bf16 v[44:47], v[72:75], v[164:167], v[44:47]
	v_mfma_f32_16x16x32_bf16 v[36:39], v[108:111], v[160:163], 0
	v_mfma_f32_16x16x32_bf16 v[36:39], v[116:119], v[164:167], v[36:39]
	v_mfma_f32_16x16x32_bf16 v[40:43], v[88:91], v[160:163], 0
	v_mfma_f32_16x16x32_bf16 v[40:43], v[96:99], v[164:167], v[40:43]
	v_mfma_f32_16x16x32_bf16 v[32:35], v[128:131], v[160:163], 0
	v_mfma_f32_16x16x32_bf16 v[32:35], v[140:143], v[164:167], v[32:35]
	v_mfma_f32_16x16x32_bf16 v[28:31], v[64:67], v[168:171], 0
	v_mfma_f32_16x16x32_bf16 v[28:31], v[72:75], v[180:183], v[28:31]
	v_mfma_f32_16x16x32_bf16 v[20:23], v[108:111], v[168:171], 0
	v_mfma_f32_16x16x32_bf16 v[20:23], v[116:119], v[180:183], v[20:23]
	v_mfma_f32_16x16x32_bf16 v[24:27], v[88:91], v[168:171], 0
	v_mfma_f32_16x16x32_bf16 v[24:27], v[96:99], v[180:183], v[24:27]
	v_mfma_f32_16x16x32_bf16 v[16:19], v[128:131], v[168:171], 0
	v_mfma_f32_16x16x32_bf16 v[16:19], v[140:143], v[180:183], v[16:19]
	v_mfma_f32_16x16x32_bf16 v[12:15], v[64:67], v[184:187], 0
	v_mfma_f32_16x16x32_bf16 v[12:15], v[72:75], v[188:191], v[12:15]
	v_mfma_f32_16x16x32_bf16 v[4:7], v[108:111], v[184:187], 0
	v_mfma_f32_16x16x32_bf16 v[4:7], v[116:119], v[188:191], v[4:7]
	v_mfma_f32_16x16x32_bf16 v[8:11], v[88:91], v[184:187], 0
	v_mfma_f32_16x16x32_bf16 v[8:11], v[96:99], v[188:191], v[8:11]
	v_mfma_f32_16x16x32_bf16 v[0:3], v[128:131], v[184:187], 0
	v_mfma_f32_16x16x32_bf16 v[0:3], v[140:143], v[188:191], v[0:3]
	s_barrier
	s_add_i32 s67, 0, 0x18000
	s_add_i32 s3, 0, 0x1c000
	ds_read_b128 v[64:67], v192 offset:32768
	ds_read_b128 v[72:75], v192 offset:33792
	ds_read_b128 v[88:91], v192 offset:34816
	ds_read_b128 v[96:99], v192 offset:35840
	ds_read_b128 v[108:111], v192 offset:49152
	ds_read_b128 v[116:119], v192 offset:50176
	ds_read_b128 v[128:131], v192 offset:51200
	ds_read_b128 v[140:143], v192 offset:52224
	s_add_u32 s74, s92, 0x80000
	s_addc_u32 s75, s93, 0
	s_mov_b32 m0, s34
	ds_read_b128 v[152:155], v240 offset:32768
	ds_read_b128 v[156:159], v240 offset:33792
	ds_read_b128 v[160:163], v240 offset:34816
	ds_read_b128 v[164:167], v240 offset:35840
	ds_read_b128 v[168:171], v240 offset:36864
	ds_read_b128 v[180:183], v240 offset:37888
	ds_read_b128 v[184:187], v240 offset:38912
	ds_read_b128 v[188:191], v240 offset:39936
	global_load_lds_dwordx4 v224, s[74:75]
	s_mov_b32 m0, s35
	s_nop 0
	global_load_lds_dwordx4 v226, s[74:75]
	s_waitcnt vmcnt(8)
	s_waitcnt lgkmcnt(0)
	s_barrier
	s_waitcnt lgkmcnt(0)
	v_mfma_f32_16x16x32_bf16 v[176:179], v[64:67], v[152:155], v[176:179]
	v_mfma_f32_16x16x32_bf16 v[176:179], v[72:75], v[156:159], v[176:179]
	v_mfma_f32_16x16x32_bf16 v[148:151], v[108:111], v[152:155], v[148:151]
	v_mfma_f32_16x16x32_bf16 v[148:151], v[116:119], v[156:159], v[148:151]
	v_mfma_f32_16x16x32_bf16 v[172:175], v[88:91], v[152:155], v[172:175]
	v_mfma_f32_16x16x32_bf16 v[172:175], v[96:99], v[156:159], v[172:175]
	v_mfma_f32_16x16x32_bf16 v[144:147], v[128:131], v[152:155], v[144:147]
	v_mfma_f32_16x16x32_bf16 v[144:147], v[140:143], v[156:159], v[144:147]
	v_mfma_f32_16x16x32_bf16 v[136:139], v[64:67], v[160:163], v[136:139]
	v_mfma_f32_16x16x32_bf16 v[136:139], v[72:75], v[164:167], v[136:139]
	v_mfma_f32_16x16x32_bf16 v[124:127], v[108:111], v[160:163], v[124:127]
	v_mfma_f32_16x16x32_bf16 v[124:127], v[116:119], v[164:167], v[124:127]
	v_mfma_f32_16x16x32_bf16 v[132:135], v[88:91], v[160:163], v[132:135]
	v_mfma_f32_16x16x32_bf16 v[132:135], v[96:99], v[164:167], v[132:135]
	v_mfma_f32_16x16x32_bf16 v[120:123], v[128:131], v[160:163], v[120:123]
	v_mfma_f32_16x16x32_bf16 v[120:123], v[140:143], v[164:167], v[120:123]
	v_mfma_f32_16x16x32_bf16 v[112:115], v[64:67], v[168:171], v[112:115]
	v_mfma_f32_16x16x32_bf16 v[112:115], v[72:75], v[180:183], v[112:115]
	v_mfma_f32_16x16x32_bf16 v[100:103], v[108:111], v[168:171], v[100:103]
	v_mfma_f32_16x16x32_bf16 v[100:103], v[116:119], v[180:183], v[100:103]
	v_mfma_f32_16x16x32_bf16 v[104:107], v[88:91], v[168:171], v[104:107]
	v_mfma_f32_16x16x32_bf16 v[104:107], v[96:99], v[180:183], v[104:107]
	v_mfma_f32_16x16x32_bf16 v[92:95], v[128:131], v[168:171], v[92:95]
	v_mfma_f32_16x16x32_bf16 v[92:95], v[140:143], v[180:183], v[92:95]
	v_mfma_f32_16x16x32_bf16 v[84:87], v[64:67], v[184:187], v[84:87]
	v_mfma_f32_16x16x32_bf16 v[84:87], v[72:75], v[188:191], v[84:87]
	v_mfma_f32_16x16x32_bf16 v[76:79], v[108:111], v[184:187], v[76:79]
	v_mfma_f32_16x16x32_bf16 v[76:79], v[116:119], v[188:191], v[76:79]
	v_mfma_f32_16x16x32_bf16 v[80:83], v[88:91], v[184:187], v[80:83]
	v_mfma_f32_16x16x32_bf16 v[80:83], v[96:99], v[188:191], v[80:83]
	v_mfma_f32_16x16x32_bf16 v[68:71], v[128:131], v[184:187], v[68:71]
	v_mfma_f32_16x16x32_bf16 v[68:71], v[140:143], v[188:191], v[68:71]
	s_barrier
	s_add_i32 s67, s67, s2
	s_add_u32 s98, s90, 0x80
	s_addc_u32 s99, s91, 0
	s_mov_b32 m0, s67
	ds_read_b128 v[152:155], v240 offset:49152
	ds_read_b128 v[156:159], v240 offset:50176
	ds_read_b128 v[160:163], v240 offset:51200
	ds_read_b128 v[164:167], v240 offset:52224
	ds_read_b128 v[168:171], v240 offset:53248
	ds_read_b128 v[180:183], v240 offset:54272
	ds_read_b128 v[184:187], v240 offset:55296
	ds_read_b128 v[188:191], v240 offset:56320
	global_load_lds_dwordx4 v216, s[98:99]
	s_add_i32 m0, s67, 0x2000
	s_add_u32 s74, s90, 0x80080
	s_addc_u32 s75, s91, 0
	s_add_i32 s3, s3, s2
	global_load_lds_dwordx4 v228, s[98:99]
	s_mov_b32 m0, s3
	s_nop 0
	global_load_lds_dwordx4 v216, s[74:75]
	s_add_i32 m0, s3, 0x2000
	s_nop 0
	global_load_lds_dwordx4 v228, s[74:75]
	s_add_u32 s98, s92, 0x80
	s_addc_u32 s99, s93, 0
	s_mov_b32 m0, s60
	s_nop 0
	global_load_lds_dwordx4 v224, s[98:99]
	s_mov_b32 m0, s61
	s_nop 0
	global_load_lds_dwordx4 v226, s[98:99]
	s_waitcnt vmcnt(8)
	s_waitcnt lgkmcnt(0)
	s_barrier
	s_waitcnt lgkmcnt(0)
	v_mfma_f32_16x16x32_bf16 v[60:63], v[64:67], v[152:155], v[60:63]
	v_mfma_f32_16x16x32_bf16 v[60:63], v[72:75], v[156:159], v[60:63]
	v_mfma_f32_16x16x32_bf16 v[52:55], v[108:111], v[152:155], v[52:55]
	v_mfma_f32_16x16x32_bf16 v[52:55], v[116:119], v[156:159], v[52:55]
	v_mfma_f32_16x16x32_bf16 v[56:59], v[88:91], v[152:155], v[56:59]
	v_mfma_f32_16x16x32_bf16 v[56:59], v[96:99], v[156:159], v[56:59]
	v_mfma_f32_16x16x32_bf16 v[48:51], v[128:131], v[152:155], v[48:51]
	v_mfma_f32_16x16x32_bf16 v[48:51], v[140:143], v[156:159], v[48:51]
	v_mfma_f32_16x16x32_bf16 v[44:47], v[64:67], v[160:163], v[44:47]
	v_mfma_f32_16x16x32_bf16 v[44:47], v[72:75], v[164:167], v[44:47]
	v_mfma_f32_16x16x32_bf16 v[36:39], v[108:111], v[160:163], v[36:39]
	v_mfma_f32_16x16x32_bf16 v[36:39], v[116:119], v[164:167], v[36:39]
	v_mfma_f32_16x16x32_bf16 v[40:43], v[88:91], v[160:163], v[40:43]
	v_mfma_f32_16x16x32_bf16 v[40:43], v[96:99], v[164:167], v[40:43]
	v_mfma_f32_16x16x32_bf16 v[32:35], v[128:131], v[160:163], v[32:35]
	v_mfma_f32_16x16x32_bf16 v[32:35], v[140:143], v[164:167], v[32:35]
	v_mfma_f32_16x16x32_bf16 v[28:31], v[64:67], v[168:171], v[28:31]
	v_mfma_f32_16x16x32_bf16 v[28:31], v[72:75], v[180:183], v[28:31]
	v_mfma_f32_16x16x32_bf16 v[20:23], v[108:111], v[168:171], v[20:23]
	v_mfma_f32_16x16x32_bf16 v[20:23], v[116:119], v[180:183], v[20:23]
	v_mfma_f32_16x16x32_bf16 v[24:27], v[88:91], v[168:171], v[24:27]
	v_mfma_f32_16x16x32_bf16 v[24:27], v[96:99], v[180:183], v[24:27]
	v_mfma_f32_16x16x32_bf16 v[16:19], v[128:131], v[168:171], v[16:19]
	v_mfma_f32_16x16x32_bf16 v[16:19], v[140:143], v[180:183], v[16:19]
	v_mfma_f32_16x16x32_bf16 v[12:15], v[64:67], v[184:187], v[12:15]
	v_mfma_f32_16x16x32_bf16 v[12:15], v[72:75], v[188:191], v[12:15]
	v_mfma_f32_16x16x32_bf16 v[4:7], v[108:111], v[184:187], v[4:7]
	v_mfma_f32_16x16x32_bf16 v[4:7], v[116:119], v[188:191], v[4:7]
	v_mfma_f32_16x16x32_bf16 v[8:11], v[88:91], v[184:187], v[8:11]
	v_mfma_f32_16x16x32_bf16 v[8:11], v[96:99], v[188:191], v[8:11]
	v_mfma_f32_16x16x32_bf16 v[0:3], v[128:131], v[184:187], v[0:3]
	v_mfma_f32_16x16x32_bf16 v[0:3], v[140:143], v[188:191], v[0:3]
	s_barrier
	s_add_i32 s71, s71, 2
	s_add_u32 s88, s88, 0x100
	s_addc_u32 s89, s89, 0
	s_add_u32 s87, s87, 0x100
	s_addc_u32 vcc_hi, vcc_hi, 0

.LBB0_1179:
	v_add_u32_e32 v177, 0x10000, v192
	ds_read_b128 v[64:67], v177
	ds_read_b128 v[68:71], v177 offset:1024
	ds_read_b128 v[72:75], v177 offset:2048
	ds_read_b128 v[76:79], v177 offset:3072
	ds_read_b128 v[80:83], v177 offset:16384
	ds_read_b128 v[116:119], v177 offset:17408
	ds_read_b128 v[152:155], v177 offset:18432
	ds_read_b128 v[156:159], v177 offset:19456
	ds_read_b128 v[160:163], v193
	ds_read_b128 v[164:167], v193 offset:1024
	ds_read_b128 v[168:171], v193 offset:2048
	ds_read_b128 v[172:175], v193 offset:3072
	ds_read_b128 v[194:197], v193 offset:4096
	ds_read_b128 v[198:201], v193 offset:5120
	ds_read_b128 v[202:205], v193 offset:6144
	ds_read_b128 v[206:209], v193 offset:7168
	s_add_i32 s68, s23, 1
	s_mul_i32 s4, s68, s61
	s_mul_hi_u32 s5, s68, s0
	s_add_i32 s5, s5, s4
	s_mul_i32 s4, s68, s0
	s_add_u32 s76, s4, s1
	s_addc_u32 s77, s5, s26
	v_mov_b64_e32 v[0:1], 0x1760
	v_cmp_lt_i64_e64 s[4:5], s[76:77], v[0:1]
	v_mov_b64_e32 v[0:1], 0x175f
	v_cmp_gt_i64_e32 vcc, s[76:77], v[0:1]
	s_cbranch_vccnz .LBB0_1181
	s_ashr_i32 s22, s76, 31
	s_lshr_b32 s22, s22, 29
	s_add_i32 s22, s76, s22
	s_ashr_i32 s67, s22, 3
	s_and_b32 s22, s22, -8
	s_sub_i32 s22, s76, s22
	s_cmp_lt_i32 s22, 0
	s_movk_i32 s70, 0x2ed
	s_cselect_b32 s70, s70, 0x2ec
	s_mul_i32 s22, s22, s70
	s_add_i32 s22, s22, s67
	s_mul_hi_i32 s67, s22, 0x2e8ba2e9
	s_lshr_b32 s70, s67, 31
	s_ashr_i32 s67, s67, 5
	s_add_i32 s67, s67, s70
	s_lshl_b32 s70, s67, 2
	s_sub_i32 s71, 0x88, s70
	s_min_i32 s71, s71, 4
	s_abs_i32 s72, s71
	v_cvt_f32_u32_e32 v0, s72
	s_sub_i32 s74, 0, s72
	s_mulk_i32 s67, 0xb0
	s_sub_i32 s67, s22, s67
	v_rcp_iflag_f32_e32 v0, v0
	s_abs_i32 s22, s67
	s_xor_b32 s73, s67, s71
	s_ashr_i32 s73, s73, 31
	v_mul_f32_e32 v0, 0x4f7ffffe, v0
	v_cvt_u32_f32_e32 v0, v0
	s_nop 0
	v_readfirstlane_b32 s75, v0
	s_mul_i32 s74, s74, s75
	s_mul_hi_u32 s74, s75, s74
	s_add_i32 s75, s75, s74
	s_mul_hi_u32 s74, s22, s75
	s_mul_i32 s75, s74, s72
	s_sub_i32 s22, s22, s75
	s_add_i32 s76, s74, 1
	s_sub_i32 s75, s22, s72
	s_cmp_ge_u32 s22, s72
	s_cselect_b32 s74, s76, s74
	s_cselect_b32 s22, s75, s22
	s_add_i32 s75, s74, 1
	s_cmp_ge_u32 s22, s72
	s_cselect_b32 s22, s75, s74
	s_xor_b32 s22, s22, s73
	s_sub_i32 s22, s22, s73
	s_mul_i32 s71, s22, s71
	s_sub_i32 s67, s67, s71
	s_add_i32 s74, s70, s67

.LBB0_1189:
	s_ashr_i32 s75, s74, 31
	s_lshl_b64 s[72:73], s[74:75], 20
	s_add_u32 s76, s2, s72
	s_addc_u32 s77, s3, s73
	s_and_b64 s[72:73], s[4:5], exec
	s_cselect_b32 s71, s77, s83
	s_cselect_b32 s72, s76, s82
	s_ashr_i32 s23, s22, 31
	s_lshl_b64 s[78:79], s[22:23], 20
	s_add_u32 s78, s14, s78
	s_addc_u32 s79, s15, s79
	s_and_b64 s[86:87], s[4:5], exec
	s_cselect_b32 s23, s79, s85
	s_cselect_b32 s73, s78, s84
	s_add_u32 s82, s82, 0x80080
	s_addc_u32 s83, s83, 0
	s_add_u32 s75, s84, 0x100
	s_addc_u32 s81, s85, 0
	s_mov_b32 s88, -2
	s_add_u32 s67, s82, 0xfff80080
	s_addc_u32 s84, s83, -1
	s_add_i32 s89, 0, 0x10000
	s_cmp_eq_u32 s88, 28
	s_cselect_b32 s87, s71, s84
	s_cselect_b32 s86, s72, s67
	s_cselect_b32 s85, s23, s81
	s_cselect_b32 s84, s73, s75
	s_add_i32 s67, 0, 0x14000
	s_add_i32 m0, s28, 0xc000
	global_load_lds_dwordx4 v186, s[82:83]
	s_add_i32 m0, s28, 0xe000
	s_nop 0
	global_load_lds_dwordx4 v188, s[82:83]
	s_waitcnt vmcnt(8)
	s_waitcnt lgkmcnt(0)
	s_barrier
	s_waitcnt lgkmcnt(0)
	v_mfma_f32_16x16x32_bf16 v[148:151], v[64:67], v[160:163], 0
	v_mfma_f32_16x16x32_bf16 v[148:151], v[68:71], v[164:167], v[148:151]
	v_mfma_f32_16x16x32_bf16 v[140:143], v[80:83], v[160:163], 0
	v_mfma_f32_16x16x32_bf16 v[140:143], v[116:119], v[164:167], v[140:143]
	v_mfma_f32_16x16x32_bf16 v[144:147], v[72:75], v[160:163], 0
	v_mfma_f32_16x16x32_bf16 v[144:147], v[76:79], v[164:167], v[144:147]
	v_mfma_f32_16x16x32_bf16 v[136:139], v[152:155], v[160:163], 0
	v_mfma_f32_16x16x32_bf16 v[136:139], v[156:159], v[164:167], v[136:139]
	v_mfma_f32_16x16x32_bf16 v[132:135], v[64:67], v[168:171], 0
	v_mfma_f32_16x16x32_bf16 v[132:135], v[68:71], v[172:175], v[132:135]
	v_mfma_f32_16x16x32_bf16 v[124:127], v[80:83], v[168:171], 0
	v_mfma_f32_16x16x32_bf16 v[124:127], v[116:119], v[172:175], v[124:127]
	v_mfma_f32_16x16x32_bf16 v[128:131], v[72:75], v[168:171], 0
	v_mfma_f32_16x16x32_bf16 v[128:131], v[76:79], v[172:175], v[128:131]
	v_mfma_f32_16x16x32_bf16 v[120:123], v[152:155], v[168:171], 0
	v_mfma_f32_16x16x32_bf16 v[120:123], v[156:159], v[172:175], v[120:123]
	v_mfma_f32_16x16x32_bf16 v[112:115], v[64:67], v[194:197], 0
	v_mfma_f32_16x16x32_bf16 v[112:115], v[68:71], v[198:201], v[112:115]
	v_mfma_f32_16x16x32_bf16 v[104:107], v[80:83], v[194:197], 0
	v_mfma_f32_16x16x32_bf16 v[104:107], v[116:119], v[198:201], v[104:107]
	v_mfma_f32_16x16x32_bf16 v[108:111], v[72:75], v[194:197], 0
	v_mfma_f32_16x16x32_bf16 v[108:111], v[76:79], v[198:201], v[108:111]
	v_mfma_f32_16x16x32_bf16 v[100:103], v[152:155], v[194:197], 0
	v_mfma_f32_16x16x32_bf16 v[100:103], v[156:159], v[198:201], v[100:103]
	v_mfma_f32_16x16x32_bf16 v[96:99], v[64:67], v[202:205], 0
	v_mfma_f32_16x16x32_bf16 v[96:99], v[68:71], v[206:209], v[96:99]
	v_mfma_f32_16x16x32_bf16 v[88:91], v[80:83], v[202:205], 0
	v_mfma_f32_16x16x32_bf16 v[88:91], v[116:119], v[206:209], v[88:91]
	v_mfma_f32_16x16x32_bf16 v[92:95], v[72:75], v[202:205], 0
	v_mfma_f32_16x16x32_bf16 v[92:95], v[76:79], v[206:209], v[92:95]
	v_mfma_f32_16x16x32_bf16 v[84:87], v[152:155], v[202:205], 0
	v_mfma_f32_16x16x32_bf16 v[84:87], v[156:159], v[206:209], v[84:87]
	s_barrier
	s_add_i32 s89, s89, s24
	s_mov_b32 m0, s89
	ds_read_b128 v[160:163], v193 offset:16384
	ds_read_b128 v[164:167], v193 offset:17408
	ds_read_b128 v[168:171], v193 offset:18432
	ds_read_b128 v[172:175], v193 offset:19456
	ds_read_b128 v[194:197], v193 offset:20480
	ds_read_b128 v[198:201], v193 offset:21504
	ds_read_b128 v[202:205], v193 offset:22528
	ds_read_b128 v[206:209], v193 offset:23552
	global_load_lds_dwordx4 v180, s[84:85]
	s_add_i32 m0, s89, 0x2000
	s_add_u32 s90, s84, 0x80000
	s_addc_u32 s91, s85, 0
	s_add_i32 s67, s67, s24
	global_load_lds_dwordx4 v176, s[84:85]
	s_mov_b32 m0, s67
	s_nop 0
	global_load_lds_dwordx4 v180, s[90:91]
	s_add_i32 m0, s67, 0x2000
	s_nop 0
	global_load_lds_dwordx4 v176, s[90:91]
	s_mov_b32 m0, s28
	s_nop 0
	global_load_lds_dwordx4 v182, s[86:87]
	s_mov_b32 m0, s29
	s_nop 0
	global_load_lds_dwordx4 v178, s[86:87]
	s_waitcnt vmcnt(8)
	s_waitcnt lgkmcnt(0)
	s_barrier
	s_waitcnt lgkmcnt(0)
	v_mfma_f32_16x16x32_bf16 v[60:63], v[64:67], v[160:163], 0
	v_mfma_f32_16x16x32_bf16 v[60:63], v[68:71], v[164:167], v[60:63]
	v_mfma_f32_16x16x32_bf16 v[52:55], v[80:83], v[160:163], 0
	v_mfma_f32_16x16x32_bf16 v[52:55], v[116:119], v[164:167], v[52:55]
	v_mfma_f32_16x16x32_bf16 v[56:59], v[72:75], v[160:163], 0
	v_mfma_f32_16x16x32_bf16 v[56:59], v[76:79], v[164:167], v[56:59]
	v_mfma_f32_16x16x32_bf16 v[48:51], v[152:155], v[160:163], 0
	v_mfma_f32_16x16x32_bf16 v[48:51], v[156:159], v[164:167], v[48:51]
	v_mfma_f32_16x16x32_bf16 v[44:47], v[64:67], v[168:171], 0
	v_mfma_f32_16x16x32_bf16 v[44:47], v[68:71], v[172:175], v[44:47]
	v_mfma_f32_16x16x32_bf16 v[36:39], v[80:83], v[168:171], 0
	v_mfma_f32_16x16x32_bf16 v[36:39], v[116:119], v[172:175], v[36:39]
	v_mfma_f32_16x16x32_bf16 v[40:43], v[72:75], v[168:171], 0
	v_mfma_f32_16x16x32_bf16 v[40:43], v[76:79], v[172:175], v[40:43]
	v_mfma_f32_16x16x32_bf16 v[32:35], v[152:155], v[168:171], 0
	v_mfma_f32_16x16x32_bf16 v[32:35], v[156:159], v[172:175], v[32:35]
	v_mfma_f32_16x16x32_bf16 v[28:31], v[64:67], v[194:197], 0
	v_mfma_f32_16x16x32_bf16 v[28:31], v[68:71], v[198:201], v[28:31]
	v_mfma_f32_16x16x32_bf16 v[20:23], v[80:83], v[194:197], 0
	v_mfma_f32_16x16x32_bf16 v[20:23], v[116:119], v[198:201], v[20:23]
	v_mfma_f32_16x16x32_bf16 v[24:27], v[72:75], v[194:197], 0
	v_mfma_f32_16x16x32_bf16 v[24:27], v[76:79], v[198:201], v[24:27]
	v_mfma_f32_16x16x32_bf16 v[16:19], v[152:155], v[194:197], 0
	v_mfma_f32_16x16x32_bf16 v[16:19], v[156:159], v[198:201], v[16:19]
	v_mfma_f32_16x16x32_bf16 v[12:15], v[64:67], v[202:205], 0
	v_mfma_f32_16x16x32_bf16 v[12:15], v[68:71], v[206:209], v[12:15]
	v_mfma_f32_16x16x32_bf16 v[4:7], v[80:83], v[202:205], 0
	v_mfma_f32_16x16x32_bf16 v[4:7], v[116:119], v[206:209], v[4:7]
	v_mfma_f32_16x16x32_bf16 v[8:11], v[72:75], v[202:205], 0
	v_mfma_f32_16x16x32_bf16 v[8:11], v[76:79], v[206:209], v[8:11]
	v_mfma_f32_16x16x32_bf16 v[0:3], v[152:155], v[202:205], 0
	v_mfma_f32_16x16x32_bf16 v[0:3], v[156:159], v[206:209], v[0:3]
	s_barrier
	s_add_i32 s67, 0, 0x18000
	s_add_i32 s89, 0, 0x1c000
	ds_read_b128 v[64:67], v177 offset:32768
	ds_read_b128 v[68:71], v177 offset:33792
	ds_read_b128 v[72:75], v177 offset:34816
	ds_read_b128 v[76:79], v177 offset:35840
	ds_read_b128 v[80:83], v177 offset:49152
	ds_read_b128 v[116:119], v177 offset:50176
	ds_read_b128 v[152:155], v177 offset:51200
	ds_read_b128 v[156:159], v177 offset:52224
	s_add_u32 s86, s86, 0x80000
	s_addc_u32 s87, s87, 0
	s_mov_b32 m0, s34
	ds_read_b128 v[160:163], v193 offset:32768
	ds_read_b128 v[164:167], v193 offset:33792
	ds_read_b128 v[168:171], v193 offset:34816
	ds_read_b128 v[172:175], v193 offset:35840
	ds_read_b128 v[194:197], v193 offset:36864
	ds_read_b128 v[198:201], v193 offset:37888
	ds_read_b128 v[202:205], v193 offset:38912
	ds_read_b128 v[206:209], v193 offset:39936
	global_load_lds_dwordx4 v182, s[86:87]
	s_mov_b32 m0, s35
	s_nop 0
	global_load_lds_dwordx4 v178, s[86:87]
	s_waitcnt vmcnt(8)
	s_waitcnt lgkmcnt(0)
	s_barrier
	s_waitcnt lgkmcnt(0)
	v_mfma_f32_16x16x32_bf16 v[148:151], v[64:67], v[160:163], v[148:151]
	v_mfma_f32_16x16x32_bf16 v[148:151], v[68:71], v[164:167], v[148:151]
	v_mfma_f32_16x16x32_bf16 v[140:143], v[80:83], v[160:163], v[140:143]
	v_mfma_f32_16x16x32_bf16 v[140:143], v[116:119], v[164:167], v[140:143]
	v_mfma_f32_16x16x32_bf16 v[144:147], v[72:75], v[160:163], v[144:147]
	v_mfma_f32_16x16x32_bf16 v[144:147], v[76:79], v[164:167], v[144:147]
	v_mfma_f32_16x16x32_bf16 v[136:139], v[152:155], v[160:163], v[136:139]
	v_mfma_f32_16x16x32_bf16 v[136:139], v[156:159], v[164:167], v[136:139]
	v_mfma_f32_16x16x32_bf16 v[132:135], v[64:67], v[168:171], v[132:135]
	v_mfma_f32_16x16x32_bf16 v[132:135], v[68:71], v[172:175], v[132:135]
	v_mfma_f32_16x16x32_bf16 v[124:127], v[80:83], v[168:171], v[124:127]
	v_mfma_f32_16x16x32_bf16 v[124:127], v[116:119], v[172:175], v[124:127]
	v_mfma_f32_16x16x32_bf16 v[128:131], v[72:75], v[168:171], v[128:131]
	v_mfma_f32_16x16x32_bf16 v[128:131], v[76:79], v[172:175], v[128:131]
	v_mfma_f32_16x16x32_bf16 v[120:123], v[152:155], v[168:171], v[120:123]
	v_mfma_f32_16x16x32_bf16 v[120:123], v[156:159], v[172:175], v[120:123]
	v_mfma_f32_16x16x32_bf16 v[112:115], v[64:67], v[194:197], v[112:115]
	v_mfma_f32_16x16x32_bf16 v[112:115], v[68:71], v[198:201], v[112:115]
	v_mfma_f32_16x16x32_bf16 v[104:107], v[80:83], v[194:197], v[104:107]
	v_mfma_f32_16x16x32_bf16 v[104:107], v[116:119], v[198:201], v[104:107]
	v_mfma_f32_16x16x32_bf16 v[108:111], v[72:75], v[194:197], v[108:111]
	v_mfma_f32_16x16x32_bf16 v[108:111], v[76:79], v[198:201], v[108:111]
	v_mfma_f32_16x16x32_bf16 v[100:103], v[152:155], v[194:197], v[100:103]
	v_mfma_f32_16x16x32_bf16 v[100:103], v[156:159], v[198:201], v[100:103]
	v_mfma_f32_16x16x32_bf16 v[96:99], v[64:67], v[202:205], v[96:99]
	v_mfma_f32_16x16x32_bf16 v[96:99], v[68:71], v[206:209], v[96:99]
	v_mfma_f32_16x16x32_bf16 v[88:91], v[80:83], v[202:205], v[88:91]
	v_mfma_f32_16x16x32_bf16 v[88:91], v[116:119], v[206:209], v[88:91]
	v_mfma_f32_16x16x32_bf16 v[92:95], v[72:75], v[202:205], v[92:95]
	v_mfma_f32_16x16x32_bf16 v[92:95], v[76:79], v[206:209], v[92:95]
	v_mfma_f32_16x16x32_bf16 v[84:87], v[152:155], v[202:205], v[84:87]
	v_mfma_f32_16x16x32_bf16 v[84:87], v[156:159], v[206:209], v[84:87]
	s_barrier
	s_add_i32 s67, s67, s24
	s_add_u32 s98, s84, 0x80
	s_addc_u32 s99, s85, 0
	s_mov_b32 m0, s67
	ds_read_b128 v[160:163], v193 offset:49152
	ds_read_b128 v[164:167], v193 offset:50176
	ds_read_b128 v[168:171], v193 offset:51200
	ds_read_b128 v[172:175], v193 offset:52224
	ds_read_b128 v[194:197], v193 offset:53248
	ds_read_b128 v[198:201], v193 offset:54272
	ds_read_b128 v[202:205], v193 offset:55296
	ds_read_b128 v[206:209], v193 offset:56320
	global_load_lds_dwordx4 v180, s[98:99]
	s_add_i32 m0, s67, 0x2000
	s_add_u32 s84, s84, 0x80080
	s_addc_u32 s85, s85, 0
	s_add_i32 s67, s89, s24
	global_load_lds_dwordx4 v176, s[98:99]
	s_mov_b32 m0, s67
	s_nop 0
	global_load_lds_dwordx4 v180, s[84:85]
	s_add_i32 m0, s67, 0x2000
	s_nop 0
	global_load_lds_dwordx4 v176, s[84:85]
	s_add_u32 s98, s86, 0xfff80080
	s_addc_u32 s99, s87, -1
	s_mov_b32 m0, s53
	s_nop 0
	global_load_lds_dwordx4 v182, s[98:99]
	s_mov_b32 m0, s54
	s_nop 0
	global_load_lds_dwordx4 v178, s[98:99]
	s_waitcnt vmcnt(8)
	s_waitcnt lgkmcnt(0)
	s_barrier
	s_waitcnt lgkmcnt(0)
	v_mfma_f32_16x16x32_bf16 v[60:63], v[64:67], v[160:163], v[60:63]
	v_mfma_f32_16x16x32_bf16 v[60:63], v[68:71], v[164:167], v[60:63]
	v_mfma_f32_16x16x32_bf16 v[52:55], v[80:83], v[160:163], v[52:55]
	v_mfma_f32_16x16x32_bf16 v[52:55], v[116:119], v[164:167], v[52:55]
	v_mfma_f32_16x16x32_bf16 v[56:59], v[72:75], v[160:163], v[56:59]
	v_mfma_f32_16x16x32_bf16 v[56:59], v[76:79], v[164:167], v[56:59]
	v_mfma_f32_16x16x32_bf16 v[48:51], v[152:155], v[160:163], v[48:51]
	v_mfma_f32_16x16x32_bf16 v[48:51], v[156:159], v[164:167], v[48:51]
	v_mfma_f32_16x16x32_bf16 v[44:47], v[64:67], v[168:171], v[44:47]
	v_mfma_f32_16x16x32_bf16 v[44:47], v[68:71], v[172:175], v[44:47]
	v_mfma_f32_16x16x32_bf16 v[36:39], v[80:83], v[168:171], v[36:39]
	v_mfma_f32_16x16x32_bf16 v[36:39], v[116:119], v[172:175], v[36:39]
	v_mfma_f32_16x16x32_bf16 v[40:43], v[72:75], v[168:171], v[40:43]
	v_mfma_f32_16x16x32_bf16 v[40:43], v[76:79], v[172:175], v[40:43]
	v_mfma_f32_16x16x32_bf16 v[32:35], v[152:155], v[168:171], v[32:35]
	v_mfma_f32_16x16x32_bf16 v[32:35], v[156:159], v[172:175], v[32:35]
	v_mfma_f32_16x16x32_bf16 v[28:31], v[64:67], v[194:197], v[28:31]
	v_mfma_f32_16x16x32_bf16 v[28:31], v[68:71], v[198:201], v[28:31]
	v_mfma_f32_16x16x32_bf16 v[20:23], v[80:83], v[194:197], v[20:23]
	v_mfma_f32_16x16x32_bf16 v[20:23], v[116:119], v[198:201], v[20:23]
	v_mfma_f32_16x16x32_bf16 v[24:27], v[72:75], v[194:197], v[24:27]
	v_mfma_f32_16x16x32_bf16 v[24:27], v[76:79], v[198:201], v[24:27]
	v_mfma_f32_16x16x32_bf16 v[16:19], v[152:155], v[194:197], v[16:19]
	v_mfma_f32_16x16x32_bf16 v[16:19], v[156:159], v[198:201], v[16:19]
	v_mfma_f32_16x16x32_bf16 v[12:15], v[64:67], v[202:205], v[12:15]
	v_mfma_f32_16x16x32_bf16 v[12:15], v[68:71], v[206:209], v[12:15]
	v_mfma_f32_16x16x32_bf16 v[4:7], v[80:83], v[202:205], v[4:7]
	v_mfma_f32_16x16x32_bf16 v[4:7], v[116:119], v[206:209], v[4:7]
	v_mfma_f32_16x16x32_bf16 v[8:11], v[72:75], v[202:205], v[8:11]
	v_mfma_f32_16x16x32_bf16 v[8:11], v[76:79], v[206:209], v[8:11]
	v_mfma_f32_16x16x32_bf16 v[0:3], v[152:155], v[202:205], v[0:3]
	v_mfma_f32_16x16x32_bf16 v[0:3], v[156:159], v[206:209], v[0:3]
	s_barrier
	s_add_i32 s88, s88, 2
	s_add_u32 s82, s82, 0x100
	s_addc_u32 s83, s83, 0
	s_add_u32 s75, s75, 0x100
	s_addc_u32 s81, s81, 0

.LBB0_1271:
	v_add_u32_e32 v192, 0x10000, v238
	ds_read_b128 v[64:67], v192
	ds_read_b128 v[72:75], v192 offset:1024
	ds_read_b128 v[88:91], v192 offset:2048
	ds_read_b128 v[96:99], v192 offset:3072
	ds_read_b128 v[108:111], v192 offset:16384
	ds_read_b128 v[116:119], v192 offset:17408
	ds_read_b128 v[128:131], v192 offset:18432
	ds_read_b128 v[140:143], v192 offset:19456
	ds_read_b128 v[152:155], v240
	ds_read_b128 v[156:159], v240 offset:1024
	ds_read_b128 v[160:163], v240 offset:2048
	ds_read_b128 v[164:167], v240 offset:3072
	ds_read_b128 v[168:171], v240 offset:4096
	ds_read_b128 v[180:183], v240 offset:5120
	ds_read_b128 v[184:187], v240 offset:6144
	ds_read_b128 v[188:191], v240 offset:7168
	s_mov_b64 s[4:5], 0
	s_andn2_b64 vcc, exec, s[10:11]
	s_mov_b64 s[74:75], 0
	s_mov_b64 s[76:77], s[16:17]
	s_cbranch_vccz .LBB0_1273
	s_andn2_b64 vcc, exec, s[76:77]
	s_add_i32 s54, s81, 1
	s_cbranch_vccz .LBB0_1274
	s_branch .LBB0_1276

.LBB0_1289:
	s_lshl_b32 s80, s96, 8
	s_ashr_i32 s81, s80, 31
	s_lshl_b64 s[86:87], s[80:81], 2
	s_add_u32 s84, s84, s86
	s_addc_u32 s85, s85, s87
	s_add_i32 m0, s94, s41
	s_add_u32 s81, s82, 0x100
	global_load_lds_dwordx4 v239, s[84:85]
	s_addc_u32 s96, s83, 0
	s_cmp_eq_u32 s54, 5
	s_cselect_b32 vcc_lo, 66, -2
	s_bfe_u32 s86, s1, 0x20003
	s_cmp_eq_u32 s86, 3
	s_cselect_b32 s86, -8, 0
	s_cmp_eq_u32 s54, 5
	s_cselect_b32 s86, s86, 0
	s_add_i32 vcc_lo, vcc_lo, s86
	s_add_u32 s82, s78, 0x100
	s_addc_u32 s83, s79, 0
	s_add_i32 s94, 0, 0x10000
	s_cmpk_eq_i32 vcc_lo, 0x54
	s_cselect_b32 s87, s75, s83
	s_cselect_b32 s86, s74, s82
	s_cselect_b32 s85, s77, s96
	s_cselect_b32 s84, s76, s81
	s_add_i32 vcc_hi, 0, 0x14000
	s_add_i32 m0, s29, 0xc000
	global_load_lds_dwordx4 v230, s[78:79]
	s_add_i32 m0, s29, 0xe000
	s_nop 0
	global_load_lds_dwordx4 v232, s[78:79]
	s_waitcnt vmcnt(8)
	s_waitcnt lgkmcnt(0)
	s_barrier
	s_waitcnt lgkmcnt(0)
	v_mfma_f32_16x16x32_bf16 v[176:179], v[64:67], v[152:155], 0
	v_mfma_f32_16x16x32_bf16 v[176:179], v[72:75], v[156:159], v[176:179]
	v_mfma_f32_16x16x32_bf16 v[148:151], v[108:111], v[152:155], 0
	v_mfma_f32_16x16x32_bf16 v[148:151], v[116:119], v[156:159], v[148:151]
	v_mfma_f32_16x16x32_bf16 v[172:175], v[88:91], v[152:155], 0
	v_mfma_f32_16x16x32_bf16 v[172:175], v[96:99], v[156:159], v[172:175]
	v_mfma_f32_16x16x32_bf16 v[144:147], v[128:131], v[152:155], 0
	v_mfma_f32_16x16x32_bf16 v[144:147], v[140:143], v[156:159], v[144:147]
	v_mfma_f32_16x16x32_bf16 v[136:139], v[64:67], v[160:163], 0
	v_mfma_f32_16x16x32_bf16 v[136:139], v[72:75], v[164:167], v[136:139]
	v_mfma_f32_16x16x32_bf16 v[124:127], v[108:111], v[160:163], 0
	v_mfma_f32_16x16x32_bf16 v[124:127], v[116:119], v[164:167], v[124:127]
	v_mfma_f32_16x16x32_bf16 v[132:135], v[88:91], v[160:163], 0
	v_mfma_f32_16x16x32_bf16 v[132:135], v[96:99], v[164:167], v[132:135]
	v_mfma_f32_16x16x32_bf16 v[120:123], v[128:131], v[160:163], 0
	v_mfma_f32_16x16x32_bf16 v[120:123], v[140:143], v[164:167], v[120:123]
	v_mfma_f32_16x16x32_bf16 v[112:115], v[64:67], v[168:171], 0
	v_mfma_f32_16x16x32_bf16 v[112:115], v[72:75], v[180:183], v[112:115]
	v_mfma_f32_16x16x32_bf16 v[100:103], v[108:111], v[168:171], 0
	v_mfma_f32_16x16x32_bf16 v[100:103], v[116:119], v[180:183], v[100:103]
	v_mfma_f32_16x16x32_bf16 v[104:107], v[88:91], v[168:171], 0
	v_mfma_f32_16x16x32_bf16 v[104:107], v[96:99], v[180:183], v[104:107]
	v_mfma_f32_16x16x32_bf16 v[92:95], v[128:131], v[168:171], 0
	v_mfma_f32_16x16x32_bf16 v[92:95], v[140:143], v[180:183], v[92:95]
	v_mfma_f32_16x16x32_bf16 v[84:87], v[64:67], v[184:187], 0
	v_mfma_f32_16x16x32_bf16 v[84:87], v[72:75], v[188:191], v[84:87]
	v_mfma_f32_16x16x32_bf16 v[76:79], v[108:111], v[184:187], 0
	v_mfma_f32_16x16x32_bf16 v[76:79], v[116:119], v[188:191], v[76:79]
	v_mfma_f32_16x16x32_bf16 v[80:83], v[88:91], v[184:187], 0
	v_mfma_f32_16x16x32_bf16 v[80:83], v[96:99], v[188:191], v[80:83]
	v_mfma_f32_16x16x32_bf16 v[68:71], v[128:131], v[184:187], 0
	v_mfma_f32_16x16x32_bf16 v[68:71], v[140:143], v[188:191], v[68:71]
	s_barrier
	s_add_i32 s78, s94, s2
	s_mov_b32 m0, s78
	ds_read_b128 v[152:155], v240 offset:16384
	ds_read_b128 v[156:159], v240 offset:17408
	ds_read_b128 v[160:163], v240 offset:18432
	ds_read_b128 v[164:167], v240 offset:19456
	ds_read_b128 v[168:171], v240 offset:20480
	ds_read_b128 v[180:183], v240 offset:21504
	ds_read_b128 v[184:187], v240 offset:22528
	ds_read_b128 v[188:191], v240 offset:23552
	global_load_lds_dwordx4 v216, s[84:85]
	s_add_i32 m0, s78, 0x2000
	s_add_u32 s78, s84, 0x160000
	s_addc_u32 s79, s85, 0
	s_add_i32 s94, vcc_hi, s2
	global_load_lds_dwordx4 v228, s[84:85]
	s_mov_b32 m0, s94
	s_nop 0
	global_load_lds_dwordx4 v216, s[78:79]
	s_add_i32 m0, s94, 0x2000
	s_nop 0
	global_load_lds_dwordx4 v228, s[78:79]
	s_mov_b32 m0, s29
	s_nop 0
	global_load_lds_dwordx4 v224, s[86:87]
	s_mov_b32 m0, s34
	s_nop 0
	global_load_lds_dwordx4 v226, s[86:87]
	s_waitcnt vmcnt(8)
	s_waitcnt lgkmcnt(0)
	s_barrier
	s_waitcnt lgkmcnt(0)
	v_mfma_f32_16x16x32_bf16 v[60:63], v[64:67], v[152:155], 0
	v_mfma_f32_16x16x32_bf16 v[60:63], v[72:75], v[156:159], v[60:63]
	v_mfma_f32_16x16x32_bf16 v[52:55], v[108:111], v[152:155], 0
	v_mfma_f32_16x16x32_bf16 v[52:55], v[116:119], v[156:159], v[52:55]
	v_mfma_f32_16x16x32_bf16 v[56:59], v[88:91], v[152:155], 0
	v_mfma_f32_16x16x32_bf16 v[56:59], v[96:99], v[156:159], v[56:59]
	v_mfma_f32_16x16x32_bf16 v[48:51], v[128:131], v[152:155], 0
	v_mfma_f32_16x16x32_bf16 v[48:51], v[140:143], v[156:159], v[48:51]
	v_mfma_f32_16x16x32_bf16 v[44:47], v[64:67], v[160:163], 0
	v_mfma_f32_16x16x32_bf16 v[44:47], v[72:75], v[164:167], v[44:47]
	v_mfma_f32_16x16x32_bf16 v[36:39], v[108:111], v[160:163], 0
	v_mfma_f32_16x16x32_bf16 v[36:39], v[116:119], v[164:167], v[36:39]
	v_mfma_f32_16x16x32_bf16 v[40:43], v[88:91], v[160:163], 0
	v_mfma_f32_16x16x32_bf16 v[40:43], v[96:99], v[164:167], v[40:43]
	v_mfma_f32_16x16x32_bf16 v[32:35], v[128:131], v[160:163], 0
	v_mfma_f32_16x16x32_bf16 v[32:35], v[140:143], v[164:167], v[32:35]
	v_mfma_f32_16x16x32_bf16 v[28:31], v[64:67], v[168:171], 0
	v_mfma_f32_16x16x32_bf16 v[28:31], v[72:75], v[180:183], v[28:31]
	v_mfma_f32_16x16x32_bf16 v[20:23], v[108:111], v[168:171], 0
	v_mfma_f32_16x16x32_bf16 v[20:23], v[116:119], v[180:183], v[20:23]
	v_mfma_f32_16x16x32_bf16 v[24:27], v[88:91], v[168:171], 0
	v_mfma_f32_16x16x32_bf16 v[24:27], v[96:99], v[180:183], v[24:27]
	v_mfma_f32_16x16x32_bf16 v[16:19], v[128:131], v[168:171], 0
	v_mfma_f32_16x16x32_bf16 v[16:19], v[140:143], v[180:183], v[16:19]
	v_mfma_f32_16x16x32_bf16 v[12:15], v[64:67], v[184:187], 0
	v_mfma_f32_16x16x32_bf16 v[12:15], v[72:75], v[188:191], v[12:15]
	v_mfma_f32_16x16x32_bf16 v[4:7], v[108:111], v[184:187], 0
	v_mfma_f32_16x16x32_bf16 v[4:7], v[116:119], v[188:191], v[4:7]
	v_mfma_f32_16x16x32_bf16 v[8:11], v[88:91], v[184:187], 0
	v_mfma_f32_16x16x32_bf16 v[8:11], v[96:99], v[188:191], v[8:11]
	v_mfma_f32_16x16x32_bf16 v[0:3], v[128:131], v[184:187], 0
	v_mfma_f32_16x16x32_bf16 v[0:3], v[140:143], v[188:191], v[0:3]
	s_barrier
	s_add_i32 s94, 0, 0x18000
	s_add_i32 vcc_hi, 0, 0x1c000
	ds_read_b128 v[64:67], v192 offset:32768
	ds_read_b128 v[72:75], v192 offset:33792
	ds_read_b128 v[88:91], v192 offset:34816
	ds_read_b128 v[96:99], v192 offset:35840
	ds_read_b128 v[108:111], v192 offset:49152
	ds_read_b128 v[116:119], v192 offset:50176
	ds_read_b128 v[128:131], v192 offset:51200
	ds_read_b128 v[140:143], v192 offset:52224
	s_add_u32 s78, s86, 0x160000
	s_addc_u32 s79, s87, 0
	s_mov_b32 m0, s35
	ds_read_b128 v[152:155], v240 offset:32768
	ds_read_b128 v[156:159], v240 offset:33792
	ds_read_b128 v[160:163], v240 offset:34816
	ds_read_b128 v[164:167], v240 offset:35840
	ds_read_b128 v[168:171], v240 offset:36864
	ds_read_b128 v[180:183], v240 offset:37888
	ds_read_b128 v[184:187], v240 offset:38912
	ds_read_b128 v[188:191], v240 offset:39936
	global_load_lds_dwordx4 v224, s[78:79]
	s_mov_b32 m0, s38
	s_nop 0
	global_load_lds_dwordx4 v226, s[78:79]
	s_waitcnt vmcnt(8)
	s_waitcnt lgkmcnt(0)
	s_barrier
	s_waitcnt lgkmcnt(0)
	v_mfma_f32_16x16x32_bf16 v[176:179], v[64:67], v[152:155], v[176:179]
	v_mfma_f32_16x16x32_bf16 v[176:179], v[72:75], v[156:159], v[176:179]
	v_mfma_f32_16x16x32_bf16 v[148:151], v[108:111], v[152:155], v[148:151]
	v_mfma_f32_16x16x32_bf16 v[148:151], v[116:119], v[156:159], v[148:151]
	v_mfma_f32_16x16x32_bf16 v[172:175], v[88:91], v[152:155], v[172:175]
	v_mfma_f32_16x16x32_bf16 v[172:175], v[96:99], v[156:159], v[172:175]
	v_mfma_f32_16x16x32_bf16 v[144:147], v[128:131], v[152:155], v[144:147]
	v_mfma_f32_16x16x32_bf16 v[144:147], v[140:143], v[156:159], v[144:147]
	v_mfma_f32_16x16x32_bf16 v[136:139], v[64:67], v[160:163], v[136:139]
	v_mfma_f32_16x16x32_bf16 v[136:139], v[72:75], v[164:167], v[136:139]
	v_mfma_f32_16x16x32_bf16 v[124:127], v[108:111], v[160:163], v[124:127]
	v_mfma_f32_16x16x32_bf16 v[124:127], v[116:119], v[164:167], v[124:127]
	v_mfma_f32_16x16x32_bf16 v[132:135], v[88:91], v[160:163], v[132:135]
	v_mfma_f32_16x16x32_bf16 v[132:135], v[96:99], v[164:167], v[132:135]
	v_mfma_f32_16x16x32_bf16 v[120:123], v[128:131], v[160:163], v[120:123]
	v_mfma_f32_16x16x32_bf16 v[120:123], v[140:143], v[164:167], v[120:123]
	v_mfma_f32_16x16x32_bf16 v[112:115], v[64:67], v[168:171], v[112:115]
	v_mfma_f32_16x16x32_bf16 v[112:115], v[72:75], v[180:183], v[112:115]
	v_mfma_f32_16x16x32_bf16 v[100:103], v[108:111], v[168:171], v[100:103]
	v_mfma_f32_16x16x32_bf16 v[100:103], v[116:119], v[180:183], v[100:103]
	v_mfma_f32_16x16x32_bf16 v[104:107], v[88:91], v[168:171], v[104:107]
	v_mfma_f32_16x16x32_bf16 v[104:107], v[96:99], v[180:183], v[104:107]
	v_mfma_f32_16x16x32_bf16 v[92:95], v[128:131], v[168:171], v[92:95]
	v_mfma_f32_16x16x32_bf16 v[92:95], v[140:143], v[180:183], v[92:95]
	v_mfma_f32_16x16x32_bf16 v[84:87], v[64:67], v[184:187], v[84:87]
	v_mfma_f32_16x16x32_bf16 v[84:87], v[72:75], v[188:191], v[84:87]
	v_mfma_f32_16x16x32_bf16 v[76:79], v[108:111], v[184:187], v[76:79]
	v_mfma_f32_16x16x32_bf16 v[76:79], v[116:119], v[188:191], v[76:79]
	v_mfma_f32_16x16x32_bf16 v[80:83], v[88:91], v[184:187], v[80:83]
	v_mfma_f32_16x16x32_bf16 v[80:83], v[96:99], v[188:191], v[80:83]
	v_mfma_f32_16x16x32_bf16 v[68:71], v[128:131], v[184:187], v[68:71]
	v_mfma_f32_16x16x32_bf16 v[68:71], v[140:143], v[188:191], v[68:71]
	s_barrier
	s_add_i32 s78, s94, s2
	s_add_u32 s98, s84, 0x80
	s_addc_u32 s99, s85, 0
	s_mov_b32 m0, s78
	ds_read_b128 v[152:155], v240 offset:49152
	ds_read_b128 v[156:159], v240 offset:50176
	ds_read_b128 v[160:163], v240 offset:51200
	ds_read_b128 v[164:167], v240 offset:52224
	ds_read_b128 v[168:171], v240 offset:53248
	ds_read_b128 v[180:183], v240 offset:54272
	ds_read_b128 v[184:187], v240 offset:55296
	ds_read_b128 v[188:191], v240 offset:56320
	global_load_lds_dwordx4 v216, s[98:99]
	s_add_i32 m0, s78, 0x2000
	s_add_u32 s78, s84, 0x160080
	s_addc_u32 s79, s85, 0
	s_add_i32 s84, vcc_hi, s2
	global_load_lds_dwordx4 v228, s[98:99]
	s_mov_b32 m0, s84
	s_nop 0
	global_load_lds_dwordx4 v216, s[78:79]
	s_add_i32 m0, s84, 0x2000
	s_nop 0
	global_load_lds_dwordx4 v228, s[78:79]
	s_add_u32 s98, s86, 0x80
	s_addc_u32 s99, s87, 0
	s_mov_b32 m0, s60
	s_nop 0
	global_load_lds_dwordx4 v224, s[98:99]
	s_mov_b32 m0, s61
	s_nop 0
	global_load_lds_dwordx4 v226, s[98:99]
	s_waitcnt vmcnt(8)
	s_waitcnt lgkmcnt(0)
	s_barrier
	s_waitcnt lgkmcnt(0)
	v_mfma_f32_16x16x32_bf16 v[60:63], v[64:67], v[152:155], v[60:63]
	v_mfma_f32_16x16x32_bf16 v[60:63], v[72:75], v[156:159], v[60:63]
	v_mfma_f32_16x16x32_bf16 v[52:55], v[108:111], v[152:155], v[52:55]
	v_mfma_f32_16x16x32_bf16 v[52:55], v[116:119], v[156:159], v[52:55]
	v_mfma_f32_16x16x32_bf16 v[56:59], v[88:91], v[152:155], v[56:59]
	v_mfma_f32_16x16x32_bf16 v[56:59], v[96:99], v[156:159], v[56:59]
	v_mfma_f32_16x16x32_bf16 v[48:51], v[128:131], v[152:155], v[48:51]
	v_mfma_f32_16x16x32_bf16 v[48:51], v[140:143], v[156:159], v[48:51]
	v_mfma_f32_16x16x32_bf16 v[44:47], v[64:67], v[160:163], v[44:47]
	v_mfma_f32_16x16x32_bf16 v[44:47], v[72:75], v[164:167], v[44:47]
	v_mfma_f32_16x16x32_bf16 v[36:39], v[108:111], v[160:163], v[36:39]
	v_mfma_f32_16x16x32_bf16 v[36:39], v[116:119], v[164:167], v[36:39]
	v_mfma_f32_16x16x32_bf16 v[40:43], v[88:91], v[160:163], v[40:43]
	v_mfma_f32_16x16x32_bf16 v[40:43], v[96:99], v[164:167], v[40:43]
	v_mfma_f32_16x16x32_bf16 v[32:35], v[128:131], v[160:163], v[32:35]
	v_mfma_f32_16x16x32_bf16 v[32:35], v[140:143], v[164:167], v[32:35]
	v_mfma_f32_16x16x32_bf16 v[28:31], v[64:67], v[168:171], v[28:31]
	v_mfma_f32_16x16x32_bf16 v[28:31], v[72:75], v[180:183], v[28:31]
	v_mfma_f32_16x16x32_bf16 v[20:23], v[108:111], v[168:171], v[20:23]
	v_mfma_f32_16x16x32_bf16 v[20:23], v[116:119], v[180:183], v[20:23]
	v_mfma_f32_16x16x32_bf16 v[24:27], v[88:91], v[168:171], v[24:27]
	v_mfma_f32_16x16x32_bf16 v[24:27], v[96:99], v[180:183], v[24:27]
	v_mfma_f32_16x16x32_bf16 v[16:19], v[128:131], v[168:171], v[16:19]
	v_mfma_f32_16x16x32_bf16 v[16:19], v[140:143], v[180:183], v[16:19]
	v_mfma_f32_16x16x32_bf16 v[12:15], v[64:67], v[184:187], v[12:15]
	v_mfma_f32_16x16x32_bf16 v[12:15], v[72:75], v[188:191], v[12:15]
	v_mfma_f32_16x16x32_bf16 v[4:7], v[108:111], v[184:187], v[4:7]
	v_mfma_f32_16x16x32_bf16 v[4:7], v[116:119], v[188:191], v[4:7]
	v_mfma_f32_16x16x32_bf16 v[8:11], v[88:91], v[184:187], v[8:11]
	v_mfma_f32_16x16x32_bf16 v[8:11], v[96:99], v[188:191], v[8:11]
	v_mfma_f32_16x16x32_bf16 v[0:3], v[128:131], v[184:187], v[0:3]
	v_mfma_f32_16x16x32_bf16 v[0:3], v[140:143], v[188:191], v[0:3]
	s_barrier
	s_add_i32 vcc_lo, vcc_lo, 2
	s_add_u32 s81, s81, 0x100
	s_addc_u32 s96, s96, 0
	s_mov_b64 s[78:79], s[82:83]
